# stack of small edits on the previous best: rnn2 carry compose batched, attention QK fragment ring, gate/relu2 transform interleaved with stores, short epilogue dispatch, counted conv-stage wait in rnn
# speedup vs baseline: 1.0038x; 1.0026x over previous
; #define LAS __attribute__((address_space(3)))
; DI unsigned pk2(float lo, float hi) { f32x2 v = {lo, hi}; bf16x2_t b = __builtin_convertvector(v, bf16x2_t); return __builtin_bit_cast(unsigned, b); }
; DI float bflo(unsigned u) { return __uint_as_float(u << 16); }
; DI float bfhi(unsigned u) { return __uint_as_float(u & 0xffff0000u); }
; DI void rnn_phase(LAS unsigned char* lds, bf16_t* P, const bf16_t* WaT, const bf16_t* WiT, const float* convw, const float* convb, const float* ba, const float* bi, const float* lam,
;                   f32x2* sums, unsigned* au, bool fin, int bx, int G, int tid, int wid, int lane) {
;     ...
;         {
;             f32x4 acc[4];
; #pragma unroll
;             for (int j = 0; j < 4; ++j) acc[j] = *(const LAS f32x4*)(CW + 256 + 16 * cq + 4 * j);
; #pragma unroll
;             for (int tap = 0; tap < 4; ++tap) {
;                 const u32x4 x0 = xr[tap][0], x1 = xr[tap][1];
;                 const LAS float* wp = CW + tap * 64 + 16 * cq;
;                 const f32x4 w0 = *(const LAS f32x4*)wp, w1 = *(const LAS f32x4*)(wp + 4), w2 = *(const LAS f32x4*)(wp + 8), w3 = *(const LAS f32x4*)(wp + 12);
;                 acc[0] += (f32x4){bflo(x0.x), bfhi(x0.x), bflo(x0.y), bfhi(x0.y)} * w0; acc[1] += (f32x4){bflo(x0.z), bfhi(x0.z), bflo(x0.w), bfhi(x0.w)} * w1;
;                 acc[2] += (f32x4){bflo(x1.x), bfhi(x1.x), bflo(x1.y), bfhi(x1.y)} * w2; acc[3] += (f32x4){bflo(x1.z), bfhi(x1.z), bflo(x1.w), bfhi(x1.w)} * w3;
;             }
; #pragma unroll
;             for (int j = 0; j < 4; ++j) *(LAS f32x4*)(XC + t * 64 + 16 * cq + 4 * j) = acc[j];
;             u32x4 o0, o1; o0.x = pk2(acc[0].x, acc[0].y); o0.y = pk2(acc[0].z, acc[0].w); o0.z = pk2(acc[1].x, acc[1].y); o0.w = pk2(acc[1].z, acc[1].w);
;             o1.x = pk2(acc[2].x, acc[2].y); o1.y = pk2(acc[2].z, acc[2].w); o1.z = pk2(acc[3].x, acc[3].y); o1.w = pk2(acc[3].z, acc[3].w);
;             *(LAS u32x4*)(XB + t * 72 + 16 * cq) = o0; *(LAS u32x4*)(XB + t * 72 + 16 * cq + 8) = o1;
;         }
;         if (u + G < NU) RNN_LOAD_XR(u + G);
.LBB0_350:
	v_add_u32_e32 v16, 0, v118
	v_add_u32_e32 v12, 0x1b400, v16
	v_add_u32_e32 v69, 0x1b000, v16
	ds_read_b128 v[0:3], v12
	ds_read_b128 v[4:7], v12 offset:16
	ds_read_b128 v[8:11], v12 offset:32
	ds_read_b128 v[12:15], v12 offset:48
	ds_read_b128 v[16:19], v69
	ds_read_b128 v[20:23], v69 offset:16
	ds_read_b128 v[24:27], v69 offset:32
	ds_read_b128 v[28:31], v69 offset:48
	s_waitcnt vmcnt(16) lgkmcnt(0)
	v_lshlrev_b32_e32 v82, 16, v36
	v_and_b32_e32 v83, 0xffff0000, v36
	v_lshlrev_b32_e32 v146, 16, v37
	v_and_b32_e32 v147, 0xffff0000, v37
	v_pk_fma_f32 v[18:19], v[18:19], v[146:147], v[2:3]
	v_pk_fma_f32 v[16:17], v[16:17], v[82:83], v[0:1]
	v_lshlrev_b32_e32 v0, 16, v38
	v_and_b32_e32 v1, 0xffff0000, v38
	v_lshlrev_b32_e32 v2, 16, v39
	v_and_b32_e32 v3, 0xffff0000, v39
	v_pk_fma_f32 v[22:23], v[22:23], v[2:3], v[6:7]
	v_pk_fma_f32 v[20:21], v[20:21], v[0:1], v[4:5]
	v_lshlrev_b32_e32 v0, 16, v40
	v_and_b32_e32 v1, 0xffff0000, v40
	v_lshlrev_b32_e32 v2, 16, v41
	v_and_b32_e32 v3, 0xffff0000, v41
	v_pk_fma_f32 v[26:27], v[26:27], v[2:3], v[10:11]
	v_pk_fma_f32 v[24:25], v[24:25], v[0:1], v[8:9]
	v_lshlrev_b32_e32 v0, 16, v42
	v_and_b32_e32 v1, 0xffff0000, v42
	v_lshlrev_b32_e32 v2, 16, v43
	v_and_b32_e32 v3, 0xffff0000, v43
	v_pk_fma_f32 v[30:31], v[30:31], v[2:3], v[14:15]
	v_pk_fma_f32 v[28:29], v[28:29], v[0:1], v[12:13]
	ds_read_b128 v[0:3], v69 offset:256
	ds_read_b128 v[4:7], v69 offset:272
	ds_read_b128 v[8:11], v69 offset:288
	ds_read_b128 v[12:15], v69 offset:304
	v_lshlrev_b32_e32 v82, 16, v32
	v_and_b32_e32 v83, 0xffff0000, v32
	v_lshlrev_b32_e32 v146, 16, v33
	v_and_b32_e32 v147, 0xffff0000, v33
	s_waitcnt lgkmcnt(3)
	v_pk_fma_f32 v[18:19], v[2:3], v[146:147], v[18:19]
	v_pk_fma_f32 v[16:17], v[0:1], v[82:83], v[16:17]
	v_lshlrev_b32_e32 v0, 16, v34
	v_and_b32_e32 v1, 0xffff0000, v34
	v_lshlrev_b32_e32 v2, 16, v35
	v_and_b32_e32 v3, 0xffff0000, v35
	s_waitcnt lgkmcnt(2)
	v_pk_fma_f32 v[22:23], v[6:7], v[2:3], v[22:23]
	v_pk_fma_f32 v[20:21], v[4:5], v[0:1], v[20:21]
	v_lshlrev_b32_e32 v0, 16, v44
	v_and_b32_e32 v1, 0xffff0000, v44
	v_lshlrev_b32_e32 v2, 16, v45
	v_and_b32_e32 v3, 0xffff0000, v45
	s_waitcnt lgkmcnt(1)
	v_pk_fma_f32 v[26:27], v[10:11], v[2:3], v[26:27]
	v_pk_fma_f32 v[24:25], v[8:9], v[0:1], v[24:25]
	v_lshlrev_b32_e32 v0, 16, v46
	v_and_b32_e32 v1, 0xffff0000, v46
	v_lshlrev_b32_e32 v2, 16, v47
	v_and_b32_e32 v3, 0xffff0000, v47
	s_waitcnt lgkmcnt(0)
	v_pk_fma_f32 v[30:31], v[14:15], v[2:3], v[30:31]
	v_pk_fma_f32 v[28:29], v[12:13], v[0:1], v[28:29]
	ds_read_b128 v[0:3], v69 offset:512
	ds_read_b128 v[4:7], v69 offset:528
	ds_read_b128 v[8:11], v69 offset:544
	ds_read_b128 v[12:15], v69 offset:560
	v_lshlrev_b32_e32 v82, 16, v48
	v_and_b32_e32 v83, 0xffff0000, v48
	v_lshlrev_b32_e32 v146, 16, v49
	v_and_b32_e32 v147, 0xffff0000, v49
	s_waitcnt lgkmcnt(3)
	v_pk_fma_f32 v[18:19], v[2:3], v[146:147], v[18:19]
	v_pk_fma_f32 v[16:17], v[0:1], v[82:83], v[16:17]
	v_lshlrev_b32_e32 v0, 16, v50
	v_and_b32_e32 v1, 0xffff0000, v50
	v_lshlrev_b32_e32 v2, 16, v51
	v_and_b32_e32 v3, 0xffff0000, v51
	s_waitcnt lgkmcnt(2)
	v_pk_fma_f32 v[22:23], v[6:7], v[2:3], v[22:23]
	v_pk_fma_f32 v[20:21], v[4:5], v[0:1], v[20:21]
	v_lshlrev_b32_e32 v0, 16, v52
	v_and_b32_e32 v1, 0xffff0000, v52
	v_lshlrev_b32_e32 v2, 16, v53
	v_and_b32_e32 v3, 0xffff0000, v53
	s_waitcnt lgkmcnt(1)
	v_pk_fma_f32 v[26:27], v[10:11], v[2:3], v[26:27]
	v_pk_fma_f32 v[24:25], v[8:9], v[0:1], v[24:25]
	v_lshlrev_b32_e32 v0, 16, v54
	v_and_b32_e32 v1, 0xffff0000, v54
	v_lshlrev_b32_e32 v2, 16, v55
	v_and_b32_e32 v3, 0xffff0000, v55
	s_waitcnt lgkmcnt(0)
	v_pk_fma_f32 v[30:31], v[14:15], v[2:3], v[30:31]
	v_pk_fma_f32 v[28:29], v[12:13], v[0:1], v[28:29]
	ds_read_b128 v[0:3], v69 offset:768
	ds_read_b128 v[4:7], v69 offset:784
	ds_read_b128 v[8:11], v69 offset:800
	ds_read_b128 v[12:15], v69 offset:816
	v_lshlrev_b32_e32 v82, 16, v56
	v_and_b32_e32 v83, 0xffff0000, v56
	v_lshlrev_b32_e32 v146, 16, v57
	v_and_b32_e32 v147, 0xffff0000, v57
	s_waitcnt lgkmcnt(3)
	v_pk_fma_f32 v[2:3], v[2:3], v[146:147], v[18:19]
	v_pk_fma_f32 v[0:1], v[0:1], v[82:83], v[16:17]
	v_lshlrev_b32_e32 v16, 16, v58
	v_and_b32_e32 v17, 0xffff0000, v58
	v_lshlrev_b32_e32 v18, 16, v59
	v_and_b32_e32 v19, 0xffff0000, v59
	s_add_i32 s20, s18, s29
	s_waitcnt lgkmcnt(2)
	v_pk_fma_f32 v[6:7], v[6:7], v[18:19], v[22:23]
	v_pk_fma_f32 v[4:5], v[4:5], v[16:17], v[20:21]
	v_lshlrev_b32_e32 v16, 16, v60
	v_and_b32_e32 v17, 0xffff0000, v60
	v_lshlrev_b32_e32 v18, 16, v61
	v_and_b32_e32 v19, 0xffff0000, v61
	s_cmpk_gt_i32 s20, 0x7ff
	s_waitcnt lgkmcnt(1)
	v_pk_fma_f32 v[10:11], v[10:11], v[18:19], v[26:27]
	v_pk_fma_f32 v[8:9], v[8:9], v[16:17], v[24:25]
	v_lshlrev_b32_e32 v16, 16, v62
	v_and_b32_e32 v17, 0xffff0000, v62
	v_lshlrev_b32_e32 v18, 16, v63
	v_and_b32_e32 v19, 0xffff0000, v63
	s_cselect_b64 s[30:31], -1, 0
	s_waitcnt lgkmcnt(0)
	v_pk_fma_f32 v[14:15], v[14:15], v[18:19], v[30:31]
	v_pk_fma_f32 v[12:13], v[12:13], v[16:17], v[28:29]
	ds_write_b128 v126, v[0:3]
	ds_write_b128 v126, v[4:7] offset:16
	ds_write_b128 v126, v[8:11] offset:32
	ds_write_b128 v126, v[12:15] offset:48
	v_cvt_pk_bf16_f32 v0, v0, v1
	v_cvt_pk_bf16_f32 v1, v2, v3
	v_cvt_pk_bf16_f32 v2, v4, v5
	v_cvt_pk_bf16_f32 v3, v6, v7
	s_and_b64 vcc, exec, s[30:31]
	v_cvt_pk_bf16_f32 v4, v8, v9
	v_cvt_pk_bf16_f32 v5, v10, v11
	v_cvt_pk_bf16_f32 v6, v12, v13
	v_cvt_pk_bf16_f32 v7, v14, v15
	ds_write_b128 v119, v[0:3]
	ds_write_b128 v119, v[4:7] offset:16
	s_cbranch_vccnz .LBB0_360
	s_ashr_i32 s22, s20, 10
	s_ashr_i32 s23, s22, 31
	s_lshl_b64 s[22:23], s[22:23], 13
	s_and_b32 s12, s62, 0x1f80
	v_mov_b32_e32 v34, v81
	v_mov_b32_e32 v35, v81
	v_add_u32_e32 v2, s12, v66
	s_or_b32 s22, s22, s12
	v_mov_b32_e32 v32, 0
	v_mov_b32_e32 v33, v81
	v_mov_b64_e32 v[38:39], v[34:35]
	v_mov_b64_e32 v[42:43], v[34:35]
	v_lshl_add_u64 v[0:1], s[22:23], 0, v[66:67]
	s_and_b32 s21, s25, 0x3c0
	v_cmp_lt_i32_e32 vcc, 2, v2
	v_mov_b64_e32 v[36:37], v[32:33]
	v_mov_b64_e32 v[40:41], v[32:33]
	s_and_saveexec_b64 s[38:39], vcc
	s_cbranch_execz .LBB0_353
	v_mov_b64_e32 v[4:5], s[42:43]
	v_mad_u64_u32 v[4:5], s[22:23], v0, s14, v[4:5]
	v_mov_b32_e32 v6, v5
	v_mad_u64_u32 v[6:7], s[22:23], v1, s14, v[6:7]
	v_mov_b32_e32 v5, v6
	s_lshl_b32 s88, s21, 1
	v_lshl_add_u64 v[4:5], v[4:5], 0, s[88:89]
	v_mov_b32_e32 v69, v81
	s_mov_b32 s22, 0xffff6800
	v_lshl_add_u64 v[4:5], v[4:5], 0, v[68:69]
	s_mov_b32 s23, -1
	v_lshl_add_u64 v[6:7], v[4:5], 0, s[22:23]
	v_add_co_u32_e32 v4, vcc, 0xffff6800, v4
	s_nop 1
	v_addc_co_u32_e32 v5, vcc, -1, v5, vcc
	global_load_dwordx4 v[36:39], v[4:5], off
	global_load_dwordx4 v[40:43], v[6:7], off offset:16
.LBB0_353:
	s_or_b64 exec, exec, s[38:39]
	v_mov_b64_e32 v[46:47], v[34:35]
	v_cmp_lt_i32_e32 vcc, 1, v2
	v_mov_b64_e32 v[44:45], v[32:33]
	s_and_saveexec_b64 s[38:39], vcc
	s_cbranch_execz .LBB0_355
	v_mov_b64_e32 v[4:5], s[42:43]
	v_mad_u64_u32 v[4:5], s[22:23], v0, s14, v[4:5]
	v_mov_b32_e32 v6, v5
	v_mad_u64_u32 v[6:7], s[22:23], v1, s14, v[6:7]
	v_mov_b32_e32 v5, v6
	s_lshl_b32 s88, s21, 1
	v_lshl_add_u64 v[4:5], v[4:5], 0, s[88:89]
	v_mov_b32_e32 v69, v81
	s_movk_i32 s22, 0xa400
	v_lshl_add_u64 v[4:5], v[4:5], 0, v[68:69]
	s_mov_b32 s23, -1
	v_lshl_add_u64 v[6:7], v[4:5], 0, s[22:23]
	v_add_co_u32_e32 v4, vcc, 0xffffa400, v4
	s_nop 1
	v_addc_co_u32_e32 v5, vcc, -1, v5, vcc
	global_load_dwordx4 v[32:35], v[4:5], off
	global_load_dwordx4 v[44:47], v[6:7], off offset:16
.LBB0_355:
	s_or_b64 exec, exec, s[38:39]
	v_mov_b32_e32 v80, v81
	v_mov_b32_e32 v82, v81
	v_mov_b32_e32 v83, v81
	v_mov_b64_e32 v[48:49], v[80:81]
	v_mov_b64_e32 v[52:53], v[80:81]
	v_cmp_lt_i32_e32 vcc, 0, v2
	v_mov_b64_e32 v[50:51], v[82:83]
	v_mov_b64_e32 v[54:55], v[82:83]
	s_and_saveexec_b64 s[38:39], vcc
	s_cbranch_execz .LBB0_357
	v_mov_b64_e32 v[4:5], s[42:43]
	v_mad_u64_u32 v[4:5], s[22:23], v0, s14, v[4:5]
	v_mov_b32_e32 v6, v5
	v_mad_u64_u32 v[6:7], s[22:23], v1, s14, v[6:7]
	v_mov_b32_e32 v5, v6
	s_lshl_b32 s88, s21, 1
	v_lshl_add_u64 v[4:5], v[4:5], 0, s[88:89]
	v_mov_b32_e32 v69, v81
	s_movk_i32 s22, 0xe000
	v_lshl_add_u64 v[4:5], v[4:5], 0, v[68:69]
	s_mov_b32 s23, -1
	v_lshl_add_u64 v[6:7], v[4:5], 0, s[22:23]
	v_add_co_u32_e32 v4, vcc, 0xffffe000, v4
	s_nop 1
	v_addc_co_u32_e32 v5, vcc, -1, v5, vcc
	global_load_dwordx4 v[48:51], v[4:5], off
	global_load_dwordx4 v[52:55], v[6:7], off offset:16
.LBB0_357:
	s_or_b64 exec, exec, s[38:39]
	v_cmp_lt_i32_e32 vcc, -1, v2
	v_mov_b32_e32 v63, 0
	v_mov_b32_e32 v62, 0
	v_mov_b32_e32 v61, 0
	v_mov_b32_e32 v60, 0
	v_mov_b32_e32 v59, 0
	v_mov_b32_e32 v58, 0
	v_mov_b32_e32 v57, 0
	v_mov_b32_e32 v56, 0
	s_and_saveexec_b64 s[38:39], vcc
	s_cbranch_execz .LBB0_359
	v_mov_b64_e32 v[2:3], s[42:43]
	v_mad_u64_u32 v[2:3], s[22:23], v0, s14, v[2:3]
	v_mov_b32_e32 v0, v3
	v_mad_u64_u32 v[0:1], s[22:23], v1, s14, v[0:1]
	v_mov_b32_e32 v3, v0
	s_lshl_b32 s88, s21, 1
	v_lshl_add_u64 v[0:1], v[2:3], 0, s[88:89]
	v_mov_b32_e32 v69, v81
	v_lshl_add_u64 v[0:1], v[0:1], 0, v[68:69]
	s_mov_b64 s[22:23], 0x1c00
	v_lshl_add_u64 v[2:3], v[0:1], 0, s[22:23]
	v_add_co_u32_e32 v0, vcc, 0x1000, v0
	s_nop 1
	v_addc_co_u32_e32 v1, vcc, 0, v1, vcc
	global_load_dwordx4 v[56:59], v[0:1], off offset:3072
	global_load_dwordx4 v[60:63], v[2:3], off offset:16

; #define LAS __attribute__((address_space(3)))
; DI float sigm(float x) { return __builtin_amdgcn_rcpf(1.0f + __builtin_amdgcn_exp2f(-x * LOG2E)); }
; #define MFMA32(a, b, c) __builtin_amdgcn_mfma_f32_32x32x16_bf16((a), (b), (c), 0, 0, 0)
; DI void rnn_phase(LAS unsigned char* lds, bf16_t* P, const bf16_t* WaT, const bf16_t* WiT, const float* convw, const float* convb, const float* ba, const float* bi, const float* lam,
;                   f32x2* sums, unsigned* au, bool fin, int bx, int G, int tid, int wid, int lane) {
;     ...
;         {
;             f32x16 aR, aI;
; #pragma unroll
;             for (int i = 0; i < 16; ++i) { aR[i] = 0.f; aI[i] = 0.f; }
; #pragma unroll
;             for (int s = 0; s < 4; ++s) {
;                 const bf16x8 af = *(const LAS bf16x8*)(XB + (32 * tt + l32) * 72 + 16 * s + 8 * hl);
;                 const bf16x8 bR = *(const LAS bf16x8*)(WL + (32 * nt + l32) * 72 + 16 * s + 8 * hl);
;                 const bf16x8 bI = *(const LAS bf16x8*)(WL + 64 * 72 + (32 * nt + l32) * 72 + 16 * s + 8 * hl);
;                 aR = MFMA32(af, bR, aR); aI = MFMA32(af, bI, aI);
;             }
;             const int ch = 32 * nt + l32;
;             float At = 1.f, Ht = 0.f;
; #pragma unroll
;             for (int g = 0; g < 4; ++g) {
;                 float A = 1.f, H = 0.f;
; #pragma unroll
;                 for (int q4 = 0; q4 < 4; ++q4) { const int i = 4 * g + q4, tok = 32 * tt + 8 * g + 4 * hl + q4;
;                     const float r = sigm(aR[i] + bac), ig = sigm(aI[i] + bic);
;                     const float a = __builtin_amdgcn_exp2f(k8c * r);
;                     const float uu_ = __builtin_amdgcn_sqrtf(fmaxf(1.0f - a * a, 0.f)) * ig * XC[tok * 64 + ch];
;                     { const h2_t pv = {(_Float16)(1.0f - a), (_Float16)uu_}; au[(rowbase + tok) * D + ch0 + ch] = __builtin_bit_cast(unsigned, pv); }
;                     H = a * H + uu_; A *= a; }
.LBB0_360:
	s_waitcnt lgkmcnt(0)
	s_barrier
	ds_read_b128 v[0:3], v120
	ds_read_b128 v[4:7], v121
	s_ashr_i32 s58, s18, 10
	s_waitcnt lgkmcnt(0)
	v_mfma_f32_32x32x16_bf16 v[16:31], v[0:3], v[4:7], 0
	ds_read_b128 v[4:7], v122
	ds_read_b128 v[150:153], v120 offset:32
	ds_read_b128 v[154:157], v121 offset:32
	s_bfe_u32 s21, s18, 0x60004
	s_ashr_i32 s59, s58, 31
	s_lshl_b64 s[60:61], s[58:59], 13
	s_lshl_b32 s12, s21, 7
	s_or_b32 s60, s60, s12
	s_waitcnt lgkmcnt(0)
	v_mfma_f32_32x32x16_bf16 v[0:15], v[0:3], v[4:7], 0
	s_lshl_b32 s88, s63, 2
	v_lshl_add_u64 v[82:83], v[78:79], 0, s[88:89]
	v_mfma_f32_32x32x16_bf16 v[16:31], v[150:153], v[154:157], v[16:31]
	ds_read_b128 v[154:157], v122 offset:32
	s_waitcnt lgkmcnt(0)
	v_mfma_f32_32x32x16_bf16 v[0:15], v[150:153], v[154:157], v[0:15]
	ds_read_b128 v[150:153], v120 offset:64
	ds_read_b128 v[154:157], v121 offset:64
	s_waitcnt lgkmcnt(0)
	v_mfma_f32_32x32x16_bf16 v[16:31], v[150:153], v[154:157], v[16:31]
	ds_read_b128 v[154:157], v120 offset:96
	ds_read_b128 v[158:161], v121 offset:96
	ds_read_b128 v[172:175], v122 offset:96
	s_waitcnt lgkmcnt(0)
	v_mfma_f32_32x32x16_bf16 v[16:31], v[154:157], v[158:161], v[16:31]
	ds_read_b128 v[158:161], v122 offset:64
	s_waitcnt lgkmcnt(0)
	v_mfma_f32_32x32x16_bf16 v[0:15], v[150:153], v[158:161], v[0:15]
	s_nop 8
	v_add_f32_e32 v16, v75, v16
	v_mul_f32_e32 v16, 0xbfb8aa3b, v16
	v_exp_f32_e32 v16, v16
	v_add_f32_e32 v17, v75, v17
	v_mul_f32_e32 v17, 0xbfb8aa3b, v17
	v_exp_f32_e32 v80, v17
	v_add_f32_e32 v16, 1.0, v16
	v_mfma_f32_32x32x16_bf16 v[0:15], v[154:157], v[172:175], v[0:15]
	v_rcp_f32_e32 v16, v16
	v_add_f32_e32 v80, 1.0, v80
	v_rcp_f32_e32 v80, v80
	ds_read_b32 v147, v127
	ds_read_b32 v149, v128
	ds_read_b32 v150, v129
	ds_read_b32 v151, v130
	ds_read_b32 v152, v131
	ds_read_b32 v153, v132
	ds_read_b32 v154, v133
	ds_read_b32 v155, v134
	v_mul_f32_e32 v16, v144, v16
	v_exp_f32_e32 v69, v16
	v_add_f32_e32 v0, v143, v0
	v_mul_f32_e32 v0, 0xbfb8aa3b, v0
	v_exp_f32_e32 v0, v0
	v_fma_f32 v16, -v69, v69, 1.0
	v_max_f32_e32 v16, 0, v16
	v_sqrt_f32_e32 v145, v16
	v_add_f32_e32 v0, 1.0, v0
	v_rcp_f32_e32 v0, v0
	v_add_f32_e32 v1, v143, v1
	v_mul_f32_e32 v1, 0xbfb8aa3b, v1
	v_lshl_add_u64 v[16:17], s[60:61], 0, v[76:77]
	v_mul_f32_e32 v0, v0, v145
	s_waitcnt lgkmcnt(0)
	v_mul_f32_e32 v145, v147, v0
	v_mul_f32_e32 v0, v144, v80
	v_exp_f32_e32 v80, v0
	v_exp_f32_e32 v147, v1
	v_lshlrev_b64 v[0:1], 12, v[16:17]
	v_sub_f32_e32 v146, 1.0, v69
	v_fma_f32 v17, -v80, v80, 1.0
	v_add_f32_e32 v16, 1.0, v147
	v_max_f32_e32 v17, 0, v17
	v_rcp_f32_e32 v16, v16
	v_sqrt_f32_e32 v17, v17
	v_cvt_pk_f16_f32 v146, v146, v145
	v_lshl_add_u64 v[0:1], v[82:83], 0, v[0:1]
	global_store_dword v[0:1], v146, off
	v_add_f32_e32 v1, v75, v18
	v_mul_f32_e32 v1, 0xbfb8aa3b, v1
	v_mul_f32_e32 v0, v16, v17
	v_exp_f32_e32 v17, v1
	v_add_f32_e32 v2, v143, v2
	v_mul_f32_e32 v2, 0xbfb8aa3b, v2
	v_exp_f32_e32 v2, v2
	v_add_f32_e32 v17, 1.0, v17
	v_rcp_f32_e32 v17, v17
	v_mul_f32_e32 v16, v149, v0
	v_sub_f32_e32 v0, 1.0, v80
	v_cvt_pk_f16_f32 v18, v0, v16
	v_mul_f32_e32 v17, v144, v17
	v_exp_f32_e32 v17, v17
	v_lshl_add_u64 v[0:1], s[60:61], 0, v[84:85]
	v_add_f32_e32 v2, 1.0, v2
	v_lshlrev_b64 v[0:1], 12, v[0:1]
	v_fma_f32 v146, -v17, v17, 1.0
	v_max_f32_e32 v146, 0, v146
	v_rcp_f32_e32 v2, v2
	v_sqrt_f32_e32 v146, v146
	v_lshl_add_u64 v[0:1], v[82:83], 0, v[0:1]
	global_store_dword v[0:1], v18, off
	v_add_f32_e32 v1, v75, v19
	v_mul_f32_e32 v1, 0xbfb8aa3b, v1
	v_mul_f32_e32 v0, v2, v146
	v_exp_f32_e32 v2, v1
	v_add_f32_e32 v3, v143, v3
	v_fmac_f32_e32 v145, 0, v69
	v_mul_f32_e32 v3, 0xbfb8aa3b, v3
	v_add_f32_e32 v2, 1.0, v2
	v_rcp_f32_e32 v2, v2
	v_fmac_f32_e32 v16, v80, v145
	v_mul_f32_e32 v18, v69, v80
	v_exp_f32_e32 v3, v3
	v_mul_f32_e32 v2, v144, v2
	v_exp_f32_e32 v80, v2
	v_mul_f32_e32 v69, v150, v0
	v_add_f32_e32 v2, 1.0, v3
	v_sub_f32_e32 v0, 1.0, v17
	v_fma_f32 v3, -v80, v80, 1.0
	v_max_f32_e32 v3, 0, v3
	v_cvt_pk_f16_f32 v19, v0, v69
	v_lshl_add_u64 v[0:1], s[60:61], 0, v[86:87]
	v_rcp_f32_e32 v2, v2
	v_sqrt_f32_e32 v3, v3
	v_lshlrev_b64 v[0:1], 12, v[0:1]
	v_lshl_add_u64 v[0:1], v[82:83], 0, v[0:1]
	global_store_dword v[0:1], v19, off
	v_fmac_f32_e32 v69, v17, v16
	v_mul_f32_e32 v1, v17, v18
	v_add_f32_e32 v17, v75, v20
	v_mul_f32_e32 v0, v2, v3
	v_mul_f32_e32 v17, 0xbfb8aa3b, v17
	v_mul_f32_e32 v0, v151, v0
	v_sub_f32_e32 v2, 1.0, v80
	v_exp_f32_e32 v17, v17
	v_cvt_pk_f16_f32 v16, v2, v0
	v_lshl_add_u64 v[2:3], s[60:61], 0, v[88:89]
	v_lshlrev_b64 v[2:3], 12, v[2:3]
	v_lshl_add_u64 v[2:3], v[82:83], 0, v[2:3]
	global_store_dword v[2:3], v16, off
	v_add_f32_e32 v2, 1.0, v17
	v_rcp_f32_e32 v2, v2
	v_add_f32_e32 v3, v143, v4
	v_mul_f32_e32 v3, 0xbfb8aa3b, v3
	v_exp_f32_e32 v3, v3
	v_mul_f32_e32 v2, v144, v2
	v_exp_f32_e32 v18, v2
	v_add_f32_e32 v5, v143, v5
	v_add_f32_e32 v2, 1.0, v3
	v_rcp_f32_e32 v4, v2
	v_fma_f32 v2, -v18, v18, 1.0
	v_max_f32_e32 v2, 0, v2
	v_sqrt_f32_e32 v16, v2
	v_fmac_f32_e32 v0, v80, v69
	v_mul_f32_e32 v5, 0xbfb8aa3b, v5
	v_add_f32_e32 v6, v143, v6
	v_mul_f32_e32 v4, v4, v16
	v_mul_f32_e32 v19, v152, v4
	v_add_f32_e32 v4, v75, v21
	v_mul_f32_e32 v4, 0xbfb8aa3b, v4
	v_exp_f32_e32 v4, v4
	v_exp_f32_e32 v21, v5
	v_sub_f32_e32 v16, 1.0, v18
	v_cvt_pk_f16_f32 v20, v16, v19
	v_add_f32_e32 v4, 1.0, v4
	v_rcp_f32_e32 v4, v4
	v_lshl_add_u64 v[16:17], s[60:61], 0, v[90:91]
	v_mul_f32_e32 v6, 0xbfb8aa3b, v6
	v_exp_f32_e32 v6, v6
	v_mul_f32_e32 v4, v144, v4
	v_exp_f32_e32 v69, v4
	v_lshlrev_b64 v[4:5], 12, v[16:17]
	v_add_f32_e32 v16, 1.0, v21
	v_rcp_f32_e32 v16, v16
	v_fma_f32 v17, -v69, v69, 1.0
	v_max_f32_e32 v17, 0, v17
	v_sqrt_f32_e32 v17, v17
; DI float sigm(float x) { return __builtin_amdgcn_rcpf(1.0f + __builtin_amdgcn_exp2f(-x * LOG2E)); }
; DI void rnn_phase(LAS unsigned char* lds, bf16_t* P, const bf16_t* WaT, const bf16_t* WiT, const float* convw, const float* convb, const float* ba, const float* bi, const float* lam,
;                   f32x2* sums, unsigned* au, bool fin, int bx, int G, int tid, int wid, int lane) {
;     ...
;                 for (int q4 = 0; q4 < 4; ++q4) { const int i = 4 * g + q4, tok = 32 * tt + 8 * g + 4 * hl + q4;
;                     const float r = sigm(aR[i] + bac), ig = sigm(aI[i] + bic);
;                     const float a = __builtin_amdgcn_exp2f(k8c * r);
;                     const float uu_ = __builtin_amdgcn_sqrtf(fmaxf(1.0f - a * a, 0.f)) * ig * XC[tok * 64 + ch];
;                     { const h2_t pv = {(_Float16)(1.0f - a), (_Float16)uu_}; au[(rowbase + tok) * D + ch0 + ch] = __builtin_bit_cast(unsigned, pv); }
;                     H = a * H + uu_; A *= a; }
	v_lshl_add_u64 v[4:5], v[82:83], 0, v[4:5]
	global_store_dword v[4:5], v20, off
	v_add_f32_e32 v5, v75, v22
	v_mul_f32_e32 v5, 0xbfb8aa3b, v5
	v_mul_f32_e32 v4, v16, v17
	v_exp_f32_e32 v17, v5
	v_mul_f32_e32 v16, v4, v153
	v_sub_f32_e32 v4, 1.0, v69
	v_cvt_pk_f16_f32 v20, v4, v16
	v_add_f32_e32 v17, 1.0, v17
	v_rcp_f32_e32 v17, v17
	v_lshl_add_u64 v[4:5], s[60:61], 0, v[92:93]
	v_add_f32_e32 v6, 1.0, v6
	v_lshlrev_b64 v[4:5], 12, v[4:5]
	v_mul_f32_e32 v17, v144, v17
	v_exp_f32_e32 v17, v17
	v_rcp_f32_e32 v6, v6
	v_lshl_add_u64 v[4:5], v[82:83], 0, v[4:5]
	global_store_dword v[4:5], v20, off
	v_fma_f32 v21, -v17, v17, 1.0
	v_max_f32_e32 v21, 0, v21
	v_sqrt_f32_e32 v21, v21
	v_add_f32_e32 v5, v75, v23
	v_mul_f32_e32 v5, 0xbfb8aa3b, v5
	v_add_f32_e32 v7, v143, v7
	v_mul_f32_e32 v4, v6, v21
	v_exp_f32_e32 v6, v5
	v_mul_f32_e32 v7, 0xbfb8aa3b, v7
	v_exp_f32_e32 v7, v7
	v_fmac_f32_e32 v19, 0, v18
	v_add_f32_e32 v6, 1.0, v6
	v_rcp_f32_e32 v6, v6
	v_fmac_f32_e32 v16, v69, v19
	v_mul_f32_e32 v19, v4, v154
	v_sub_f32_e32 v4, 1.0, v17
	v_mul_f32_e32 v6, v144, v6
	v_exp_f32_e32 v21, v6
	v_add_f32_e32 v6, 1.0, v7
	v_cvt_pk_f16_f32 v20, v4, v19
	v_lshl_add_u64 v[4:5], s[60:61], 0, v[94:95]
	v_fma_f32 v7, -v21, v21, 1.0
	v_max_f32_e32 v7, 0, v7
	v_rcp_f32_e32 v6, v6
	v_sqrt_f32_e32 v7, v7
	v_lshlrev_b64 v[4:5], 12, v[4:5]
	v_mul_f32_e32 v18, v18, v69
	v_lshl_add_u64 v[4:5], v[82:83], 0, v[4:5]
	global_store_dword v[4:5], v20, off
	v_fmac_f32_e32 v19, v17, v16
	v_mul_f32_e32 v5, v17, v18
	v_add_f32_e32 v17, v75, v24
	v_mul_f32_e32 v4, v6, v7
	v_mul_f32_e32 v17, 0xbfb8aa3b, v17
	v_mul_f32_e32 v4, v4, v155
	v_sub_f32_e32 v6, 1.0, v21
	v_exp_f32_e32 v17, v17
	v_cvt_pk_f16_f32 v16, v6, v4
	v_lshl_add_u64 v[6:7], s[60:61], 0, v[96:97]
	v_lshlrev_b64 v[6:7], 12, v[6:7]
	v_lshl_add_u64 v[6:7], v[82:83], 0, v[6:7]
	global_store_dword v[6:7], v16, off
	v_add_f32_e32 v6, 1.0, v17
	v_rcp_f32_e32 v6, v6
	v_add_f32_e32 v7, v143, v8
	v_mul_f32_e32 v7, 0xbfb8aa3b, v7
	v_exp_f32_e32 v7, v7
	v_mul_f32_e32 v6, v144, v6
	v_exp_f32_e32 v18, v6
	v_mul_f32_e32 v3, v80, v1
	v_add_f32_e32 v6, 1.0, v7
	v_rcp_f32_e32 v8, v6
	v_fma_f32 v6, -v18, v18, 1.0
	v_max_f32_e32 v6, 0, v6
	v_sqrt_f32_e32 v16, v6
	v_fmac_f32_e32 v4, v21, v19
	v_mul_f32_e32 v7, v21, v5
	v_add_f32_e32 v9, v143, v9
	v_mul_f32_e32 v8, v8, v16
	ds_read_b32 v16, v135
	ds_read_b32 v19, v136
	ds_read_b32 v20, v137
	ds_read_b32 v21, v138
	ds_read_b32 v22, v139
	ds_read_b32 v23, v140
	ds_read_b32 v24, v141
	ds_read_b32 v69, v142
	s_waitcnt lgkmcnt(0)
	v_mul_f32_e32 v80, v8, v16
	v_add_f32_e32 v8, v75, v25
	v_mul_f32_e32 v8, 0xbfb8aa3b, v8
	v_exp_f32_e32 v8, v8
	v_mul_f32_e32 v9, 0xbfb8aa3b, v9
	v_exp_f32_e32 v145, v9
	v_sub_f32_e32 v16, 1.0, v18
	v_add_f32_e32 v8, 1.0, v8
	v_rcp_f32_e32 v8, v8
	v_cvt_pk_f16_f32 v25, v16, v80
	v_lshl_add_u64 v[16:17], s[60:61], 0, v[98:99]
	v_add_f32_e32 v10, v143, v10
	v_mul_f32_e32 v8, v144, v8
	v_exp_f32_e32 v146, v8
	v_lshlrev_b64 v[8:9], 12, v[16:17]
	v_add_f32_e32 v16, 1.0, v145
	v_rcp_f32_e32 v16, v16
	v_fma_f32 v17, -v146, v146, 1.0
	v_max_f32_e32 v17, 0, v17
	v_sqrt_f32_e32 v17, v17
	v_lshl_add_u64 v[8:9], v[82:83], 0, v[8:9]
	global_store_dword v[8:9], v25, off
	v_add_f32_e32 v9, v75, v26
	v_mul_f32_e32 v9, 0xbfb8aa3b, v9
	v_mul_f32_e32 v8, v16, v17
	v_exp_f32_e32 v17, v9
	v_mul_f32_e32 v10, 0xbfb8aa3b, v10
	v_exp_f32_e32 v10, v10
	v_mul_f32_e32 v16, v8, v19
	v_add_f32_e32 v17, 1.0, v17
	v_rcp_f32_e32 v17, v17
	v_sub_f32_e32 v8, 1.0, v146
	v_cvt_pk_f16_f32 v19, v8, v16
	v_lshl_add_u64 v[8:9], s[60:61], 0, v[100:101]
	v_mul_f32_e32 v17, v144, v17
	v_exp_f32_e32 v17, v17
	v_add_f32_e32 v10, 1.0, v10
	v_lshlrev_b64 v[8:9], 12, v[8:9]
	v_rcp_f32_e32 v10, v10
	v_fma_f32 v25, -v17, v17, 1.0
	v_max_f32_e32 v25, 0, v25
	v_sqrt_f32_e32 v25, v25
	v_lshl_add_u64 v[8:9], v[82:83], 0, v[8:9]
	global_store_dword v[8:9], v19, off
	v_add_f32_e32 v9, v75, v27
	v_mul_f32_e32 v9, 0xbfb8aa3b, v9
	v_mul_f32_e32 v8, v10, v25
	v_exp_f32_e32 v10, v9
	v_add_f32_e32 v11, v143, v11
	v_mul_f32_e32 v11, 0xbfb8aa3b, v11
	v_exp_f32_e32 v11, v11
	v_add_f32_e32 v10, 1.0, v10
	v_rcp_f32_e32 v10, v10
	v_mul_f32_e32 v19, v8, v20
	v_sub_f32_e32 v8, 1.0, v17
	v_cvt_pk_f16_f32 v20, v8, v19
	v_mul_f32_e32 v10, v144, v10
	v_exp_f32_e32 v25, v10
	v_add_f32_e32 v10, 1.0, v11
	v_lshl_add_u64 v[8:9], s[60:61], 0, v[102:103]
	v_rcp_f32_e32 v10, v10
	v_fma_f32 v11, -v25, v25, 1.0
	v_max_f32_e32 v11, 0, v11
	v_sqrt_f32_e32 v11, v11
	v_fmac_f32_e32 v80, 0, v18
	v_lshlrev_b64 v[8:9], 12, v[8:9]
	v_fmac_f32_e32 v16, v146, v80
	v_mul_f32_e32 v18, v18, v146
	v_lshl_add_u64 v[8:9], v[82:83], 0, v[8:9]
	global_store_dword v[8:9], v20, off
	v_fmac_f32_e32 v19, v17, v16
	v_mul_f32_e32 v9, v17, v18
	v_add_f32_e32 v17, v75, v28
	v_mul_f32_e32 v8, v10, v11
	v_mul_f32_e32 v17, 0xbfb8aa3b, v17
	v_mul_f32_e32 v8, v8, v21
	v_sub_f32_e32 v10, 1.0, v25
	v_exp_f32_e32 v17, v17
	v_cvt_pk_f16_f32 v16, v10, v8
	v_lshl_add_u64 v[10:11], s[60:61], 0, v[104:105]
; DI float sigm(float x) { return __builtin_amdgcn_rcpf(1.0f + __builtin_amdgcn_exp2f(-x * LOG2E)); }
; DI void rnn_phase(LAS unsigned char* lds, bf16_t* P, const bf16_t* WaT, const bf16_t* WiT, const float* convw, const float* convb, const float* ba, const float* bi, const float* lam,
;                   f32x2* sums, unsigned* au, bool fin, int bx, int G, int tid, int wid, int lane) {
;     ...
;                 for (int q4 = 0; q4 < 4; ++q4) { const int i = 4 * g + q4, tok = 32 * tt + 8 * g + 4 * hl + q4;
;                     const float r = sigm(aR[i] + bac), ig = sigm(aI[i] + bic);
;                     const float a = __builtin_amdgcn_exp2f(k8c * r);
;                     const float uu_ = __builtin_amdgcn_sqrtf(fmaxf(1.0f - a * a, 0.f)) * ig * XC[tok * 64 + ch];
;                     { const h2_t pv = {(_Float16)(1.0f - a), (_Float16)uu_}; au[(rowbase + tok) * D + ch0 + ch] = __builtin_bit_cast(unsigned, pv); }
;                     H = a * H + uu_; A *= a; }
;                 const float pA = __shfl_xor(A, 32), pH = __shfl_xor(H, 32);
;                 const float fA = hl ? pA : A, fH = hl ? pH : H, sA = hl ? A : pA, sH = hl ? H : pH;
;                 Ht = fA * Ht + fH; At *= fA; Ht = sA * Ht + sH; At *= sA;
;             }
;             if (hl == 0) { SG[tt * 64 + ch] = At; SG[256 + tt * 64 + ch] = Ht; }
;             __syncthreads();
;             if (tt == 3 && hl == 0) { float Ac = 1.f, Hc = 0.f;
; #pragma unroll
;                 for (int s = 0; s < 4; ++s) { const float sa = SG[s * 64 + ch]; Hc = sa * Hc + SG[256 + s * 64 + ch]; Ac *= sa; }
;                 sums[((size_t)b * NCH + c) * D + ch0 + ch] = (f32x2){Ac, Hc}; }
	v_lshlrev_b64 v[10:11], 12, v[10:11]
	v_lshl_add_u64 v[10:11], v[82:83], 0, v[10:11]
	global_store_dword v[10:11], v16, off
	v_add_f32_e32 v10, 1.0, v17
	v_rcp_f32_e32 v10, v10
	v_add_f32_e32 v11, v143, v12
	v_mul_f32_e32 v11, 0xbfb8aa3b, v11
	v_exp_f32_e32 v11, v11
	v_mul_f32_e32 v10, v144, v10
	v_exp_f32_e32 v18, v10
	v_fmac_f32_e32 v8, v25, v19
	v_add_f32_e32 v10, 1.0, v11
	v_rcp_f32_e32 v12, v10
	v_fma_f32 v10, -v18, v18, 1.0
	v_max_f32_e32 v10, 0, v10
	v_sqrt_f32_e32 v16, v10
	v_add_f32_e32 v13, v143, v13
	v_mul_f32_e32 v13, 0xbfb8aa3b, v13
	v_exp_f32_e32 v21, v13
	v_mul_f32_e32 v12, v12, v16
	v_mul_f32_e32 v19, v12, v22
	v_add_f32_e32 v12, v75, v29
	v_mul_f32_e32 v12, 0xbfb8aa3b, v12
	v_exp_f32_e32 v12, v12
	v_sub_f32_e32 v16, 1.0, v18
	v_cvt_pk_f16_f32 v20, v16, v19
	v_lshl_add_u64 v[16:17], s[60:61], 0, v[106:107]
	v_add_f32_e32 v12, 1.0, v12
	v_rcp_f32_e32 v12, v12
	v_fmac_f32_e32 v19, 0, v18
	v_add_f32_e32 v14, v143, v14
	v_mul_f32_e32 v14, 0xbfb8aa3b, v14
	v_mul_f32_e32 v12, v144, v12
	v_exp_f32_e32 v22, v12
	v_lshlrev_b64 v[12:13], 12, v[16:17]
	v_add_f32_e32 v16, 1.0, v21
	v_rcp_f32_e32 v16, v16
	v_fma_f32 v17, -v22, v22, 1.0
	v_max_f32_e32 v17, 0, v17
	v_sqrt_f32_e32 v17, v17
	v_lshl_add_u64 v[12:13], v[82:83], 0, v[12:13]
	global_store_dword v[12:13], v20, off
	v_add_f32_e32 v13, v75, v30
	v_mul_f32_e32 v12, v16, v17
	v_mul_f32_e32 v13, 0xbfb8aa3b, v13
	v_mul_f32_e32 v16, v12, v23
	v_sub_f32_e32 v12, 1.0, v22
	v_exp_f32_e32 v17, v13
	v_cvt_pk_f16_f32 v20, v12, v16
	v_lshl_add_u64 v[12:13], s[60:61], 0, v[108:109]
	v_lshlrev_b64 v[12:13], 12, v[12:13]
	v_lshl_add_u64 v[12:13], v[82:83], 0, v[12:13]
	v_add_f32_e32 v17, 1.0, v17
	global_store_dword v[12:13], v20, off
	v_add_f32_e32 v13, v75, v31
	v_rcp_f32_e32 v17, v17
	v_mul_f32_e32 v13, 0xbfb8aa3b, v13
	v_fmac_f32_e32 v16, v22, v19
	v_exp_f32_e32 v19, v13
	v_mul_f32_e32 v17, v144, v17
	v_exp_f32_e32 v17, v17
	v_exp_f32_e32 v14, v14
	v_add_f32_e32 v19, 1.0, v19
	v_rcp_f32_e32 v19, v19
	v_fma_f32 v21, -v17, v17, 1.0
	v_add_f32_e32 v14, 1.0, v14
	v_max_f32_e32 v21, 0, v21
	v_add_f32_e32 v15, v143, v15
	v_mul_f32_e32 v19, v144, v19
	v_rcp_f32_e32 v14, v14
	v_sqrt_f32_e32 v21, v21
	v_mul_f32_e32 v15, 0xbfb8aa3b, v15
	v_exp_f32_e32 v19, v19
	v_exp_f32_e32 v15, v15
	v_mul_f32_e32 v12, v14, v21
	v_mul_f32_e32 v14, v12, v24
	v_fma_f32 v21, -v19, v19, 1.0
	v_add_f32_e32 v15, 1.0, v15
	v_max_f32_e32 v21, 0, v21
	v_sub_f32_e32 v12, 1.0, v17
	v_rcp_f32_e32 v15, v15
	v_sqrt_f32_e32 v21, v21
	v_cvt_pk_f16_f32 v20, v12, v14
	v_lshl_add_u64 v[12:13], s[60:61], 0, v[110:111]
	v_lshlrev_b64 v[12:13], 12, v[12:13]
	v_lshl_add_u64 v[12:13], v[82:83], 0, v[12:13]
	v_mul_f32_e32 v18, v18, v22
	global_store_dword v[12:13], v20, off
	v_mul_f32_e32 v12, v15, v21
	v_fmac_f32_e32 v14, v17, v16
	v_mul_f32_e32 v13, v17, v18
	v_mul_f32_e32 v12, v12, v69
	v_sub_f32_e32 v15, 1.0, v19
	v_mul_f32_e32 v11, v25, v9
	v_cvt_pk_f16_f32 v18, v15, v12
	v_fmac_f32_e32 v12, v19, v14
	v_mul_f32_e32 v15, v19, v13
	ds_bpermute_b32 v2, v123, v3
	ds_bpermute_b32 v1, v123, v0
	ds_bpermute_b32 v6, v123, v7
	ds_bpermute_b32 v5, v123, v4
	ds_bpermute_b32 v10, v123, v11
	ds_bpermute_b32 v9, v123, v8
	ds_bpermute_b32 v13, v123, v15
	ds_bpermute_b32 v14, v123, v12
	v_lshl_add_u64 v[16:17], s[60:61], 0, v[112:113]
	v_lshlrev_b64 v[16:17], 12, v[16:17]
	v_lshl_add_u64 v[16:17], v[82:83], 0, v[16:17]
	global_store_dword v[16:17], v18, off
	s_and_saveexec_b64 s[38:39], s[40:41]
	s_cbranch_execz .LBB0_362
	v_fmac_f32_e32 v0, 0, v3
	s_waitcnt lgkmcnt(0)
	v_mul_f32_e32 v16, v3, v2
	v_fmac_f32_e32 v1, v0, v2
	v_mul_f32_e32 v16, v7, v16
	v_fmac_f32_e32 v4, v7, v1
	v_mul_f32_e32 v16, v16, v6
	v_fmac_f32_e32 v5, v4, v6
	v_mul_f32_e32 v16, v11, v16
	v_fmac_f32_e32 v8, v11, v5
	v_mul_f32_e32 v16, v16, v10
	v_fmac_f32_e32 v9, v8, v10
	v_mul_f32_e32 v16, v15, v16
	v_fmac_f32_e32 v12, v15, v9
	v_mul_f32_e32 v16, v16, v13
	v_fmac_f32_e32 v14, v12, v13
	ds_write2st64_b32 v124, v16, v14 offset1:4
.LBB0_362:
	s_or_b64 exec, exec, s[38:39]
	s_waitcnt lgkmcnt(0)
	s_barrier
	s_and_saveexec_b64 s[38:39], s[56:57]
	s_cbranch_execz .LBB0_341
	ds_read2st64_b32 v[0:1], v125 offset1:1
	ds_read2st64_b32 v[2:3], v125 offset0:4 offset1:5
	ds_read2st64_b32 v[4:5], v125 offset0:6 offset1:7
	ds_read2st64_b32 v[6:7], v125 offset0:2 offset1:3
	s_lshl_b64 s[22:23], s[58:59], 19
	s_add_u32 s12, s16, s22
	s_waitcnt lgkmcnt(0)
	v_fma_f32 v2, 0, v0, v2
	v_fmac_f32_e32 v3, v2, v1
	v_fmac_f32_e32 v4, v3, v6
	s_addc_u32 s18, s17, s23
	s_lshl_b32 s21, s21, 13
	v_mul_f32_e32 v0, v0, v1
	v_mov_b32_e32 v1, v4
	v_mov_b32_e32 v4, v7
	s_add_u32 s22, s12, s21
	v_mul_f32_e32 v2, v0, v6
	v_pk_fma_f32 v[0:1], v[0:1], v[6:7], v[4:5]
	s_addc_u32 s23, s18, 0
	v_lshlrev_b32_e32 v80, 3, v74
	v_mov_b32_e32 v3, v1
	v_lshl_add_u64 v[0:1], s[22:23], 0, v[80:81]
	s_lshl_b32 s88, s63, 3
	v_mul_f32_e32 v2, v2, v7
	v_lshl_add_u64 v[0:1], v[0:1], 0, s[88:89]
	global_store_dwordx2 v[0:1], v[2:3], off
	s_branch .LBB0_341

; DI void epilogue(const f32x4 (&acc)[2][2][4][2], int ph, unsigned char* ws, const float* pscale, const Unit& u, int wr, int wc, int fr, int fq) {
;     const int row0 = u.pm * BM + wr * 64 + fr, colw = u.pn * BM + wc * 64, col0 = colw + 8 * fq;
;     const int mode = (ph == 0 || ph == 4 || ph == 7) ? EP_BF16 : ph == 2 ? EP_SCALE : ph == 3 ? EP_MERGE : EP_RELU2;
;     bf16_t* Ob = ph == 3 ? (bf16_t*)(ws + WS_MERGED) : (ph == 4 || ph == 7) ? (bf16_t*)(ws + WS_PROJ + PROJ_MIX_OFF) : (bf16_t*)(ws + WS_PROJ) + (ph == 2 ? PC_P : 0);
;     const int ldc = (ph == 0 || ph == 2) ? DIN : (ph == 6 ? DFF : D);
.LBB0_509:
	s_lshr_b32 s0, 0xd1, s6
	s_and_b32 s0, s0, 1
	s_cmp_eq_u32 s0, 0
	s_cbranch_scc1 .Ldisp_orig
	s_mov_b32 s67, s6
	v_mov_b32_e32 v80, v149
	s_cmp_eq_u32 s6, 6
	s_cselect_b32 s68, 1, 0
	s_cselect_b32 s64, s15, 0x400
	s_cmp_eq_u32 s6, 0
	s_cselect_b32 s64, 0x1e00, s64
	s_lshr_b32 s0, 0x90, s6
	s_and_b32 s0, s0, 1
	s_lshl_b32 s0, s0, 27
	s_add_u32 s0, s0, 0x10400000
	s_add_u32 s40, s46, s0
	s_addc_u32 s41, s47, 0
	v_add_u32_e32 v82, s69, v80
	s_branch .LBB0_552

; DI unsigned pk2(float lo, float hi) { f32x2 v = {lo, hi}; bf16x2_t b = __builtin_convertvector(v, bf16x2_t); return __builtin_bit_cast(unsigned, b); }
; DI unsigned ror8(unsigned x) { return (unsigned)__builtin_amdgcn_mov_dpp((int)x, 0x128, 0xf, 0xf, true); }
; DI void store_lines(bf16_t* Ob, size_t row, int ldc, int colw, int fr, int fq, const u32x4& w0, const u32x4& w1) {
;     const bool lo = (fr & 8) == 0;
;     const u32x4 snd = lo ? w1 : w0;
;     u32x4 rcv; rcv.x = ror8(snd.x); rcv.y = ror8(snd.y); rcv.z = ror8(snd.z); rcv.w = ror8(snd.w);
;     const u32x4 dA = lo ? w0 : rcv, dB = lo ? rcv : w1;
;     const int col = colw + 8 * fq + (lo ? 0 : 32);
;     __builtin_nontemporal_store(dA, (u32x4*)(Ob + (lo ? row : row - 8) * ldc + col));
;     __builtin_nontemporal_store(dB, (u32x4*)(Ob + (lo ? row + 8 : row) * ldc + col));
; DI void epilogue(const f32x4 (&acc)[2][2][4][2], int ph, unsigned char* ws, const float* pscale, const Unit& u, int wr, int wc, int fr, int fq) {
;     ...
;         const bool r2 = mode == EP_RELU2; const bool gateD = (ph == 0) && (u.pn * BM >= PC_G);
; #pragma unroll
;         for (int ai = 0; ai < 2; ++ai)
; #pragma unroll
;             for (int m = 0; m < 4; ++m) { u32x4 w[2];
; #pragma unroll
;                 for (int bj = 0; bj < 2; ++bj) { f32x4 v0 = acc[ai][bj][m][0], v1 = acc[ai][bj][m][1];
;                     if (gateD) {
; #pragma unroll
;                         for (int j = 0; j < 4; ++j) { v0[j] = 1.0f + __builtin_amdgcn_exp2f(-fmaxf(v0[j], -30.f) * LOG2E); v1[j] = 1.0f + __builtin_amdgcn_exp2f(-fmaxf(v1[j], -30.f) * LOG2E); } }
;                     if (r2) {
; #pragma unroll
;                         for (int j = 0; j < 4; ++j) { const float a = fmaxf(v0[j], 0.f), b = fmaxf(v1[j], 0.f); v0[j] = a * a; v1[j] = b * b; } }
;                     w[bj].x = pk2(v0[0], v0[1]); w[bj].y = pk2(v0[2], v0[3]); w[bj].z = pk2(v1[0], v1[1]); w[bj].w = pk2(v1[2], v1[3]); }
;                 store_lines(Ob, (size_t)(row0 + ai * HALF + m * 16), ldc, colw, fr, fq, w[0], w[1]); }
.LBB0_552:
	s_cmp_eq_u32 s67, 0
	s_cselect_b64 s[0:1], -1, 0
	s_cmp_gt_i32 s17, 17
	s_cselect_b64 s[18:19], -1, 0
	s_and_b64 s[18:19], s[0:1], s[18:19]
	s_andn2_b64 vcc, exec, s[18:19]
	s_cbranch_vccnz .Lep_nogate
	s_mov_b32 s18, 0xc1f00000
	s_mov_b32 s19, 0xbfb8aa3b
	v_and_b32_e32 v83, 8, v80
	v_sub_u32_e32 v175, v82, v83
	v_lshlrev_b32_e32 v83, 2, v83
	v_or3_b32 v132, v83, s66, v172
	v_ashrrev_i32_e32 v133, 31, v132
	v_lshl_add_u64 v[136:137], v[132:133], 1, s[40:41]
	v_mad_u64_u32 v[146:147], s[0:1], s64, v175, 0
	s_lshl_b32 s38, s64, 4
	s_mov_b32 s39, 0
	s_lshl_b32 s42, s64, 7
	s_mov_b32 s43, 0
	v_lshl_add_u64 v[146:147], v[146:147], 1, v[136:137]
	v_max_f32_e32 v128, s18, v128
	v_max_f32_e32 v129, s18, v129
	v_max_f32_e32 v130, s18, v130
	v_max_f32_e32 v131, s18, v131
	v_max_f32_e32 v124, s18, v124
	v_max_f32_e32 v125, s18, v125
	v_max_f32_e32 v126, s18, v126
	v_max_f32_e32 v127, s18, v127
	v_max_f32_e32 v120, s18, v120
	v_max_f32_e32 v121, s18, v121
	v_max_f32_e32 v122, s18, v122
	v_max_f32_e32 v123, s18, v123
	v_max_f32_e32 v116, s18, v116
	v_max_f32_e32 v117, s18, v117
	v_max_f32_e32 v118, s18, v118
	v_max_f32_e32 v119, s18, v119
	v_mul_f32_e32 v128, s19, v128
	v_mul_f32_e32 v129, s19, v129
	v_mul_f32_e32 v130, s19, v130
	v_mul_f32_e32 v131, s19, v131
	v_mul_f32_e32 v124, s19, v124
	v_mul_f32_e32 v125, s19, v125
	v_mul_f32_e32 v126, s19, v126
	v_mul_f32_e32 v127, s19, v127
	v_mul_f32_e32 v120, s19, v120
	v_mul_f32_e32 v121, s19, v121
	v_mul_f32_e32 v122, s19, v122
	v_mul_f32_e32 v123, s19, v123
	v_mul_f32_e32 v116, s19, v116
	v_mul_f32_e32 v117, s19, v117
	v_mul_f32_e32 v118, s19, v118
	v_mul_f32_e32 v119, s19, v119
	v_exp_f32_e32 v128, v128
	v_exp_f32_e32 v129, v129
	v_exp_f32_e32 v130, v130
	v_exp_f32_e32 v131, v131
	v_exp_f32_e32 v124, v124
	v_exp_f32_e32 v125, v125
	v_exp_f32_e32 v126, v126
	v_exp_f32_e32 v127, v127
	v_exp_f32_e32 v120, v120
	v_exp_f32_e32 v121, v121
	v_exp_f32_e32 v122, v122
	v_exp_f32_e32 v123, v123
	v_exp_f32_e32 v116, v116
	v_exp_f32_e32 v117, v117
	v_exp_f32_e32 v118, v118
	v_exp_f32_e32 v119, v119
	s_nop 0
	v_pk_add_f32 v[128:129], v[128:129], 1.0 op_sel_hi:[1,0]
	v_pk_add_f32 v[130:131], v[130:131], 1.0 op_sel_hi:[1,0]
	v_pk_add_f32 v[124:125], v[124:125], 1.0 op_sel_hi:[1,0]
	v_pk_add_f32 v[126:127], v[126:127], 1.0 op_sel_hi:[1,0]
	v_pk_add_f32 v[120:121], v[120:121], 1.0 op_sel_hi:[1,0]
	v_pk_add_f32 v[122:123], v[122:123], 1.0 op_sel_hi:[1,0]
	v_pk_add_f32 v[116:117], v[116:117], 1.0 op_sel_hi:[1,0]
	v_pk_add_f32 v[118:119], v[118:119], 1.0 op_sel_hi:[1,0]
	v_max_f32_e32 v112, s18, v112
	v_max_f32_e32 v113, s18, v113
	v_max_f32_e32 v114, s18, v114
	v_max_f32_e32 v115, s18, v115
	v_max_f32_e32 v108, s18, v108
	v_max_f32_e32 v109, s18, v109
	v_max_f32_e32 v110, s18, v110
	v_max_f32_e32 v111, s18, v111
	v_max_f32_e32 v104, s18, v104
	v_max_f32_e32 v105, s18, v105
	v_max_f32_e32 v106, s18, v106
	v_max_f32_e32 v107, s18, v107
	v_max_f32_e32 v100, s18, v100
	v_max_f32_e32 v101, s18, v101
	v_max_f32_e32 v102, s18, v102
	v_max_f32_e32 v103, s18, v103
	v_mul_f32_e32 v112, s19, v112
	v_mul_f32_e32 v113, s19, v113
	v_mul_f32_e32 v114, s19, v114
	v_mul_f32_e32 v115, s19, v115
	v_mul_f32_e32 v108, s19, v108
	v_mul_f32_e32 v109, s19, v109
	v_mul_f32_e32 v110, s19, v110
	v_mul_f32_e32 v111, s19, v111
	v_mul_f32_e32 v104, s19, v104
	v_mul_f32_e32 v105, s19, v105
	v_mul_f32_e32 v106, s19, v106
	v_mul_f32_e32 v107, s19, v107
	v_mul_f32_e32 v100, s19, v100
	v_mul_f32_e32 v101, s19, v101
	v_mul_f32_e32 v102, s19, v102
	v_mul_f32_e32 v103, s19, v103
	v_exp_f32_e32 v112, v112
	v_exp_f32_e32 v113, v113
	v_exp_f32_e32 v114, v114
	v_exp_f32_e32 v115, v115
	v_exp_f32_e32 v108, v108
	v_exp_f32_e32 v109, v109
	v_exp_f32_e32 v110, v110
	v_exp_f32_e32 v111, v111
	v_exp_f32_e32 v104, v104
	v_exp_f32_e32 v105, v105
	v_exp_f32_e32 v106, v106
	v_exp_f32_e32 v107, v107
	v_exp_f32_e32 v100, v100
	v_exp_f32_e32 v101, v101
	v_exp_f32_e32 v102, v102
	v_exp_f32_e32 v103, v103
	v_cvt_pk_bf16_f32 v128, v128, v129
	v_cvt_pk_bf16_f32 v129, v130, v131
	v_cvt_pk_bf16_f32 v130, v124, v125
	v_cvt_pk_bf16_f32 v131, v126, v127
	v_cvt_pk_bf16_f32 v120, v120, v121
	v_cvt_pk_bf16_f32 v121, v122, v123
	v_cvt_pk_bf16_f32 v122, v116, v117
	v_cvt_pk_bf16_f32 v123, v118, v119
	v_mov_b32_e32 v132, v128
	v_mov_b32_e32 v133, v129
	v_mov_b32_e32 v134, v130
	v_mov_b32_e32 v135, v131
	v_mov_b32_dpp v128, v120 row_ror:8 row_mask:0xf bank_mask:0xc
	v_mov_b32_dpp v129, v121 row_ror:8 row_mask:0xf bank_mask:0xc
	v_mov_b32_dpp v130, v122 row_ror:8 row_mask:0xf bank_mask:0xc
	v_mov_b32_dpp v131, v123 row_ror:8 row_mask:0xf bank_mask:0xc
	v_mov_b32_dpp v120, v132 row_ror:8 row_mask:0xf bank_mask:0x3
	v_mov_b32_dpp v121, v133 row_ror:8 row_mask:0xf bank_mask:0x3
	v_mov_b32_dpp v122, v134 row_ror:8 row_mask:0xf bank_mask:0x3
	v_mov_b32_dpp v123, v135 row_ror:8 row_mask:0xf bank_mask:0x3
	global_store_dwordx4 v[146:147], v[128:131], off nt
	v_lshl_add_u64 v[146:147], v[146:147], 0, s[38:39]
	global_store_dwordx4 v[146:147], v[120:123], off nt
	v_lshl_add_u64 v[146:147], v[146:147], 0, s[38:39]
	v_pk_add_f32 v[112:113], v[112:113], 1.0 op_sel_hi:[1,0]
	v_pk_add_f32 v[114:115], v[114:115], 1.0 op_sel_hi:[1,0]
	v_pk_add_f32 v[108:109], v[108:109], 1.0 op_sel_hi:[1,0]
	v_pk_add_f32 v[110:111], v[110:111], 1.0 op_sel_hi:[1,0]
	v_pk_add_f32 v[104:105], v[104:105], 1.0 op_sel_hi:[1,0]
	v_pk_add_f32 v[106:107], v[106:107], 1.0 op_sel_hi:[1,0]
	v_pk_add_f32 v[100:101], v[100:101], 1.0 op_sel_hi:[1,0]
	v_pk_add_f32 v[102:103], v[102:103], 1.0 op_sel_hi:[1,0]
	v_max_f32_e32 v96, s18, v96
	v_max_f32_e32 v97, s18, v97
	v_max_f32_e32 v98, s18, v98
	v_max_f32_e32 v99, s18, v99
; DI unsigned pk2(float lo, float hi) { f32x2 v = {lo, hi}; bf16x2_t b = __builtin_convertvector(v, bf16x2_t); return __builtin_bit_cast(unsigned, b); }
; DI unsigned ror8(unsigned x) { return (unsigned)__builtin_amdgcn_mov_dpp((int)x, 0x128, 0xf, 0xf, true); }
; DI void store_lines(bf16_t* Ob, size_t row, int ldc, int colw, int fr, int fq, const u32x4& w0, const u32x4& w1) {
;     const bool lo = (fr & 8) == 0;
;     const u32x4 snd = lo ? w1 : w0;
;     u32x4 rcv; rcv.x = ror8(snd.x); rcv.y = ror8(snd.y); rcv.z = ror8(snd.z); rcv.w = ror8(snd.w);
;     const u32x4 dA = lo ? w0 : rcv, dB = lo ? rcv : w1;
;     const int col = colw + 8 * fq + (lo ? 0 : 32);
;     __builtin_nontemporal_store(dA, (u32x4*)(Ob + (lo ? row : row - 8) * ldc + col));
;     __builtin_nontemporal_store(dB, (u32x4*)(Ob + (lo ? row + 8 : row) * ldc + col));
; DI void epilogue(const f32x4 (&acc)[2][2][4][2], int ph, unsigned char* ws, const float* pscale, const Unit& u, int wr, int wc, int fr, int fq) {
;     ...
;                 for (int bj = 0; bj < 2; ++bj) { f32x4 v0 = acc[ai][bj][m][0], v1 = acc[ai][bj][m][1];
;                     if (gateD) {
; #pragma unroll
;                         for (int j = 0; j < 4; ++j) { v0[j] = 1.0f + __builtin_amdgcn_exp2f(-fmaxf(v0[j], -30.f) * LOG2E); v1[j] = 1.0f + __builtin_amdgcn_exp2f(-fmaxf(v1[j], -30.f) * LOG2E); } }
;                     if (r2) {
; #pragma unroll
;                         for (int j = 0; j < 4; ++j) { const float a = fmaxf(v0[j], 0.f), b = fmaxf(v1[j], 0.f); v0[j] = a * a; v1[j] = b * b; } }
;                     w[bj].x = pk2(v0[0], v0[1]); w[bj].y = pk2(v0[2], v0[3]); w[bj].z = pk2(v1[0], v1[1]); w[bj].w = pk2(v1[2], v1[3]); }
;                 store_lines(Ob, (size_t)(row0 + ai * HALF + m * 16), ldc, colw, fr, fq, w[0], w[1]); }
	v_max_f32_e32 v92, s18, v92
	v_max_f32_e32 v93, s18, v93
	v_max_f32_e32 v94, s18, v94
	v_max_f32_e32 v95, s18, v95
	v_max_f32_e32 v88, s18, v88
	v_max_f32_e32 v89, s18, v89
	v_max_f32_e32 v90, s18, v90
	v_max_f32_e32 v91, s18, v91
	v_max_f32_e32 v84, s18, v84
	v_max_f32_e32 v85, s18, v85
	v_max_f32_e32 v86, s18, v86
	v_max_f32_e32 v87, s18, v87
	v_mul_f32_e32 v96, s19, v96
	v_mul_f32_e32 v97, s19, v97
	v_mul_f32_e32 v98, s19, v98
	v_mul_f32_e32 v99, s19, v99
	v_mul_f32_e32 v92, s19, v92
	v_mul_f32_e32 v93, s19, v93
	v_mul_f32_e32 v94, s19, v94
	v_mul_f32_e32 v95, s19, v95
	v_mul_f32_e32 v88, s19, v88
	v_mul_f32_e32 v89, s19, v89
	v_mul_f32_e32 v90, s19, v90
	v_mul_f32_e32 v91, s19, v91
	v_mul_f32_e32 v84, s19, v84
	v_mul_f32_e32 v85, s19, v85
	v_mul_f32_e32 v86, s19, v86
	v_mul_f32_e32 v87, s19, v87
	v_exp_f32_e32 v96, v96
	v_exp_f32_e32 v97, v97
	v_exp_f32_e32 v98, v98
	v_exp_f32_e32 v99, v99
	v_exp_f32_e32 v92, v92
	v_exp_f32_e32 v93, v93
	v_exp_f32_e32 v94, v94
	v_exp_f32_e32 v95, v95
	v_exp_f32_e32 v88, v88
	v_exp_f32_e32 v89, v89
	v_exp_f32_e32 v90, v90
	v_exp_f32_e32 v91, v91
	v_exp_f32_e32 v84, v84
	v_exp_f32_e32 v85, v85
	v_exp_f32_e32 v86, v86
	v_exp_f32_e32 v87, v87
	v_cvt_pk_bf16_f32 v112, v112, v113
	v_cvt_pk_bf16_f32 v113, v114, v115
	v_cvt_pk_bf16_f32 v114, v108, v109
	v_cvt_pk_bf16_f32 v115, v110, v111
	v_cvt_pk_bf16_f32 v104, v104, v105
	v_cvt_pk_bf16_f32 v105, v106, v107
	v_cvt_pk_bf16_f32 v106, v100, v101
	v_cvt_pk_bf16_f32 v107, v102, v103
	v_mov_b32_e32 v132, v112
	v_mov_b32_e32 v133, v113
	v_mov_b32_e32 v134, v114
	v_mov_b32_e32 v135, v115
	v_mov_b32_dpp v112, v104 row_ror:8 row_mask:0xf bank_mask:0xc
	v_mov_b32_dpp v113, v105 row_ror:8 row_mask:0xf bank_mask:0xc
	v_mov_b32_dpp v114, v106 row_ror:8 row_mask:0xf bank_mask:0xc
	v_mov_b32_dpp v115, v107 row_ror:8 row_mask:0xf bank_mask:0xc
	v_mov_b32_dpp v104, v132 row_ror:8 row_mask:0xf bank_mask:0x3
	v_mov_b32_dpp v105, v133 row_ror:8 row_mask:0xf bank_mask:0x3
	v_mov_b32_dpp v106, v134 row_ror:8 row_mask:0xf bank_mask:0x3
	v_mov_b32_dpp v107, v135 row_ror:8 row_mask:0xf bank_mask:0x3
	global_store_dwordx4 v[146:147], v[112:115], off nt
	v_lshl_add_u64 v[146:147], v[146:147], 0, s[38:39]
	global_store_dwordx4 v[146:147], v[104:107], off nt
	v_lshl_add_u64 v[146:147], v[146:147], 0, s[38:39]
	v_pk_add_f32 v[96:97], v[96:97], 1.0 op_sel_hi:[1,0]
	v_pk_add_f32 v[98:99], v[98:99], 1.0 op_sel_hi:[1,0]
	v_pk_add_f32 v[92:93], v[92:93], 1.0 op_sel_hi:[1,0]
	v_pk_add_f32 v[94:95], v[94:95], 1.0 op_sel_hi:[1,0]
	v_pk_add_f32 v[88:89], v[88:89], 1.0 op_sel_hi:[1,0]
	v_pk_add_f32 v[90:91], v[90:91], 1.0 op_sel_hi:[1,0]
	v_pk_add_f32 v[84:85], v[84:85], 1.0 op_sel_hi:[1,0]
	v_pk_add_f32 v[86:87], v[86:87], 1.0 op_sel_hi:[1,0]
	v_max_f32_e32 v76, s18, v76
	v_max_f32_e32 v77, s18, v77
	v_max_f32_e32 v78, s18, v78
	v_max_f32_e32 v79, s18, v79
	v_max_f32_e32 v72, s18, v72
	v_max_f32_e32 v73, s18, v73
	v_max_f32_e32 v74, s18, v74
	v_max_f32_e32 v75, s18, v75
	v_max_f32_e32 v68, s18, v68
	v_max_f32_e32 v69, s18, v69
	v_max_f32_e32 v70, s18, v70
	v_max_f32_e32 v71, s18, v71
	v_max_f32_e32 v64, s18, v64
	v_max_f32_e32 v65, s18, v65
	v_max_f32_e32 v66, s18, v66
	v_max_f32_e32 v67, s18, v67
	v_mul_f32_e32 v76, s19, v76
	v_mul_f32_e32 v77, s19, v77
	v_mul_f32_e32 v78, s19, v78
	v_mul_f32_e32 v79, s19, v79
	v_mul_f32_e32 v72, s19, v72
	v_mul_f32_e32 v73, s19, v73
	v_mul_f32_e32 v74, s19, v74
	v_mul_f32_e32 v75, s19, v75
	v_mul_f32_e32 v68, s19, v68
	v_mul_f32_e32 v69, s19, v69
	v_mul_f32_e32 v70, s19, v70
	v_mul_f32_e32 v71, s19, v71
	v_mul_f32_e32 v64, s19, v64
	v_mul_f32_e32 v65, s19, v65
	v_mul_f32_e32 v66, s19, v66
	v_mul_f32_e32 v67, s19, v67
	v_exp_f32_e32 v76, v76
	v_exp_f32_e32 v77, v77
	v_exp_f32_e32 v78, v78
	v_exp_f32_e32 v79, v79
	v_exp_f32_e32 v72, v72
	v_exp_f32_e32 v73, v73
	v_exp_f32_e32 v74, v74
	v_exp_f32_e32 v75, v75
	v_exp_f32_e32 v68, v68
	v_exp_f32_e32 v69, v69
	v_exp_f32_e32 v70, v70
	v_exp_f32_e32 v71, v71
	v_exp_f32_e32 v64, v64
	v_exp_f32_e32 v65, v65
	v_exp_f32_e32 v66, v66
	v_exp_f32_e32 v67, v67
	v_cvt_pk_bf16_f32 v96, v96, v97
	v_cvt_pk_bf16_f32 v97, v98, v99
	v_cvt_pk_bf16_f32 v98, v92, v93
	v_cvt_pk_bf16_f32 v99, v94, v95
	v_cvt_pk_bf16_f32 v88, v88, v89
	v_cvt_pk_bf16_f32 v89, v90, v91
	v_cvt_pk_bf16_f32 v90, v84, v85
	v_cvt_pk_bf16_f32 v91, v86, v87
	v_mov_b32_e32 v132, v96
	v_mov_b32_e32 v133, v97
	v_mov_b32_e32 v134, v98
	v_mov_b32_e32 v135, v99
	v_mov_b32_dpp v96, v88 row_ror:8 row_mask:0xf bank_mask:0xc
	v_mov_b32_dpp v97, v89 row_ror:8 row_mask:0xf bank_mask:0xc
	v_mov_b32_dpp v98, v90 row_ror:8 row_mask:0xf bank_mask:0xc
	v_mov_b32_dpp v99, v91 row_ror:8 row_mask:0xf bank_mask:0xc
	v_mov_b32_dpp v88, v132 row_ror:8 row_mask:0xf bank_mask:0x3
	v_mov_b32_dpp v89, v133 row_ror:8 row_mask:0xf bank_mask:0x3
	v_mov_b32_dpp v90, v134 row_ror:8 row_mask:0xf bank_mask:0x3
	v_mov_b32_dpp v91, v135 row_ror:8 row_mask:0xf bank_mask:0x3
	global_store_dwordx4 v[146:147], v[96:99], off nt
	v_lshl_add_u64 v[146:147], v[146:147], 0, s[38:39]
	global_store_dwordx4 v[146:147], v[88:91], off nt
	v_lshl_add_u64 v[146:147], v[146:147], 0, s[38:39]
	v_pk_add_f32 v[76:77], v[76:77], 1.0 op_sel_hi:[1,0]
	v_pk_add_f32 v[78:79], v[78:79], 1.0 op_sel_hi:[1,0]
	v_pk_add_f32 v[72:73], v[72:73], 1.0 op_sel_hi:[1,0]
	v_pk_add_f32 v[74:75], v[74:75], 1.0 op_sel_hi:[1,0]
	v_pk_add_f32 v[68:69], v[68:69], 1.0 op_sel_hi:[1,0]
	v_pk_add_f32 v[70:71], v[70:71], 1.0 op_sel_hi:[1,0]
	v_pk_add_f32 v[64:65], v[64:65], 1.0 op_sel_hi:[1,0]
	v_pk_add_f32 v[66:67], v[66:67], 1.0 op_sel_hi:[1,0]
	v_max_f32_e32 v60, s18, v60
	v_max_f32_e32 v61, s18, v61
	v_max_f32_e32 v62, s18, v62
; DI unsigned pk2(float lo, float hi) { f32x2 v = {lo, hi}; bf16x2_t b = __builtin_convertvector(v, bf16x2_t); return __builtin_bit_cast(unsigned, b); }
; DI unsigned ror8(unsigned x) { return (unsigned)__builtin_amdgcn_mov_dpp((int)x, 0x128, 0xf, 0xf, true); }
; DI void store_lines(bf16_t* Ob, size_t row, int ldc, int colw, int fr, int fq, const u32x4& w0, const u32x4& w1) {
;     const bool lo = (fr & 8) == 0;
;     const u32x4 snd = lo ? w1 : w0;
;     u32x4 rcv; rcv.x = ror8(snd.x); rcv.y = ror8(snd.y); rcv.z = ror8(snd.z); rcv.w = ror8(snd.w);
;     const u32x4 dA = lo ? w0 : rcv, dB = lo ? rcv : w1;
;     const int col = colw + 8 * fq + (lo ? 0 : 32);
;     __builtin_nontemporal_store(dA, (u32x4*)(Ob + (lo ? row : row - 8) * ldc + col));
;     __builtin_nontemporal_store(dB, (u32x4*)(Ob + (lo ? row + 8 : row) * ldc + col));
; DI void epilogue(const f32x4 (&acc)[2][2][4][2], int ph, unsigned char* ws, const float* pscale, const Unit& u, int wr, int wc, int fr, int fq) {
;     ...
;                 for (int bj = 0; bj < 2; ++bj) { f32x4 v0 = acc[ai][bj][m][0], v1 = acc[ai][bj][m][1];
;                     if (gateD) {
; #pragma unroll
;                         for (int j = 0; j < 4; ++j) { v0[j] = 1.0f + __builtin_amdgcn_exp2f(-fmaxf(v0[j], -30.f) * LOG2E); v1[j] = 1.0f + __builtin_amdgcn_exp2f(-fmaxf(v1[j], -30.f) * LOG2E); } }
;                     if (r2) {
; #pragma unroll
;                         for (int j = 0; j < 4; ++j) { const float a = fmaxf(v0[j], 0.f), b = fmaxf(v1[j], 0.f); v0[j] = a * a; v1[j] = b * b; } }
;                     w[bj].x = pk2(v0[0], v0[1]); w[bj].y = pk2(v0[2], v0[3]); w[bj].z = pk2(v1[0], v1[1]); w[bj].w = pk2(v1[2], v1[3]); }
;                 store_lines(Ob, (size_t)(row0 + ai * HALF + m * 16), ldc, colw, fr, fq, w[0], w[1]); }
	v_max_f32_e32 v63, s18, v63
	v_max_f32_e32 v56, s18, v56
	v_max_f32_e32 v57, s18, v57
	v_max_f32_e32 v58, s18, v58
	v_max_f32_e32 v59, s18, v59
	v_max_f32_e32 v52, s18, v52
	v_max_f32_e32 v53, s18, v53
	v_max_f32_e32 v54, s18, v54
	v_max_f32_e32 v55, s18, v55
	v_max_f32_e32 v48, s18, v48
	v_max_f32_e32 v49, s18, v49
	v_max_f32_e32 v50, s18, v50
	v_max_f32_e32 v51, s18, v51
	v_mul_f32_e32 v60, s19, v60
	v_mul_f32_e32 v61, s19, v61
	v_mul_f32_e32 v62, s19, v62
	v_mul_f32_e32 v63, s19, v63
	v_mul_f32_e32 v56, s19, v56
	v_mul_f32_e32 v57, s19, v57
	v_mul_f32_e32 v58, s19, v58
	v_mul_f32_e32 v59, s19, v59
	v_mul_f32_e32 v52, s19, v52
	v_mul_f32_e32 v53, s19, v53
	v_mul_f32_e32 v54, s19, v54
	v_mul_f32_e32 v55, s19, v55
	v_mul_f32_e32 v48, s19, v48
	v_mul_f32_e32 v49, s19, v49
	v_mul_f32_e32 v50, s19, v50
	v_mul_f32_e32 v51, s19, v51
	v_exp_f32_e32 v60, v60
	v_exp_f32_e32 v61, v61
	v_exp_f32_e32 v62, v62
	v_exp_f32_e32 v63, v63
	v_exp_f32_e32 v56, v56
	v_exp_f32_e32 v57, v57
	v_exp_f32_e32 v58, v58
	v_exp_f32_e32 v59, v59
	v_exp_f32_e32 v52, v52
	v_exp_f32_e32 v53, v53
	v_exp_f32_e32 v54, v54
	v_exp_f32_e32 v55, v55
	v_exp_f32_e32 v48, v48
	v_exp_f32_e32 v49, v49
	v_exp_f32_e32 v50, v50
	v_exp_f32_e32 v51, v51
	v_cvt_pk_bf16_f32 v76, v76, v77
	v_cvt_pk_bf16_f32 v77, v78, v79
	v_cvt_pk_bf16_f32 v78, v72, v73
	v_cvt_pk_bf16_f32 v79, v74, v75
	v_cvt_pk_bf16_f32 v68, v68, v69
	v_cvt_pk_bf16_f32 v69, v70, v71
	v_cvt_pk_bf16_f32 v70, v64, v65
	v_cvt_pk_bf16_f32 v71, v66, v67
	v_mov_b32_e32 v132, v76
	v_mov_b32_e32 v133, v77
	v_mov_b32_e32 v134, v78
	v_mov_b32_e32 v135, v79
	v_mov_b32_dpp v76, v68 row_ror:8 row_mask:0xf bank_mask:0xc
	v_mov_b32_dpp v77, v69 row_ror:8 row_mask:0xf bank_mask:0xc
	v_mov_b32_dpp v78, v70 row_ror:8 row_mask:0xf bank_mask:0xc
	v_mov_b32_dpp v79, v71 row_ror:8 row_mask:0xf bank_mask:0xc
	v_mov_b32_dpp v68, v132 row_ror:8 row_mask:0xf bank_mask:0x3
	v_mov_b32_dpp v69, v133 row_ror:8 row_mask:0xf bank_mask:0x3
	v_mov_b32_dpp v70, v134 row_ror:8 row_mask:0xf bank_mask:0x3
	v_mov_b32_dpp v71, v135 row_ror:8 row_mask:0xf bank_mask:0x3
	global_store_dwordx4 v[146:147], v[76:79], off nt
	v_lshl_add_u64 v[146:147], v[146:147], 0, s[38:39]
	global_store_dwordx4 v[146:147], v[68:71], off nt
	v_lshl_add_u64 v[146:147], v[146:147], 0, s[38:39]
	v_lshl_add_u64 v[146:147], v[146:147], 0, s[42:43]
	v_pk_add_f32 v[60:61], v[60:61], 1.0 op_sel_hi:[1,0]
	v_pk_add_f32 v[62:63], v[62:63], 1.0 op_sel_hi:[1,0]
	v_pk_add_f32 v[56:57], v[56:57], 1.0 op_sel_hi:[1,0]
	v_pk_add_f32 v[58:59], v[58:59], 1.0 op_sel_hi:[1,0]
	v_pk_add_f32 v[52:53], v[52:53], 1.0 op_sel_hi:[1,0]
	v_pk_add_f32 v[54:55], v[54:55], 1.0 op_sel_hi:[1,0]
	v_pk_add_f32 v[48:49], v[48:49], 1.0 op_sel_hi:[1,0]
	v_pk_add_f32 v[50:51], v[50:51], 1.0 op_sel_hi:[1,0]
	v_max_f32_e32 v44, s18, v44
	v_max_f32_e32 v45, s18, v45
	v_max_f32_e32 v46, s18, v46
	v_max_f32_e32 v47, s18, v47
	v_max_f32_e32 v40, s18, v40
	v_max_f32_e32 v41, s18, v41
	v_max_f32_e32 v42, s18, v42
	v_max_f32_e32 v43, s18, v43
	v_max_f32_e32 v36, s18, v36
	v_max_f32_e32 v37, s18, v37
	v_max_f32_e32 v38, s18, v38
	v_max_f32_e32 v39, s18, v39
	v_max_f32_e32 v32, s18, v32
	v_max_f32_e32 v33, s18, v33
	v_max_f32_e32 v34, s18, v34
	v_max_f32_e32 v35, s18, v35
	v_mul_f32_e32 v44, s19, v44
	v_mul_f32_e32 v45, s19, v45
	v_mul_f32_e32 v46, s19, v46
	v_mul_f32_e32 v47, s19, v47
	v_mul_f32_e32 v40, s19, v40
	v_mul_f32_e32 v41, s19, v41
	v_mul_f32_e32 v42, s19, v42
	v_mul_f32_e32 v43, s19, v43
	v_mul_f32_e32 v36, s19, v36
	v_mul_f32_e32 v37, s19, v37
	v_mul_f32_e32 v38, s19, v38
	v_mul_f32_e32 v39, s19, v39
	v_mul_f32_e32 v32, s19, v32
	v_mul_f32_e32 v33, s19, v33
	v_mul_f32_e32 v34, s19, v34
	v_mul_f32_e32 v35, s19, v35
	v_exp_f32_e32 v44, v44
	v_exp_f32_e32 v45, v45
	v_exp_f32_e32 v46, v46
	v_exp_f32_e32 v47, v47
	v_exp_f32_e32 v40, v40
	v_exp_f32_e32 v41, v41
	v_exp_f32_e32 v42, v42
	v_exp_f32_e32 v43, v43
	v_exp_f32_e32 v36, v36
	v_exp_f32_e32 v37, v37
	v_exp_f32_e32 v38, v38
	v_exp_f32_e32 v39, v39
	v_exp_f32_e32 v32, v32
	v_exp_f32_e32 v33, v33
	v_exp_f32_e32 v34, v34
	v_exp_f32_e32 v35, v35
	v_cvt_pk_bf16_f32 v60, v60, v61
	v_cvt_pk_bf16_f32 v61, v62, v63
	v_cvt_pk_bf16_f32 v62, v56, v57
	v_cvt_pk_bf16_f32 v63, v58, v59
	v_cvt_pk_bf16_f32 v52, v52, v53
	v_cvt_pk_bf16_f32 v53, v54, v55
	v_cvt_pk_bf16_f32 v54, v48, v49
	v_cvt_pk_bf16_f32 v55, v50, v51
	v_mov_b32_e32 v132, v60
	v_mov_b32_e32 v133, v61
	v_mov_b32_e32 v134, v62
	v_mov_b32_e32 v135, v63
	v_mov_b32_dpp v60, v52 row_ror:8 row_mask:0xf bank_mask:0xc
	v_mov_b32_dpp v61, v53 row_ror:8 row_mask:0xf bank_mask:0xc
	v_mov_b32_dpp v62, v54 row_ror:8 row_mask:0xf bank_mask:0xc
	v_mov_b32_dpp v63, v55 row_ror:8 row_mask:0xf bank_mask:0xc
	v_mov_b32_dpp v52, v132 row_ror:8 row_mask:0xf bank_mask:0x3
	v_mov_b32_dpp v53, v133 row_ror:8 row_mask:0xf bank_mask:0x3
	v_mov_b32_dpp v54, v134 row_ror:8 row_mask:0xf bank_mask:0x3
	v_mov_b32_dpp v55, v135 row_ror:8 row_mask:0xf bank_mask:0x3
	global_store_dwordx4 v[146:147], v[60:63], off nt
	v_lshl_add_u64 v[146:147], v[146:147], 0, s[38:39]
	global_store_dwordx4 v[146:147], v[52:55], off nt
	v_lshl_add_u64 v[146:147], v[146:147], 0, s[38:39]
	v_pk_add_f32 v[44:45], v[44:45], 1.0 op_sel_hi:[1,0]
	v_pk_add_f32 v[46:47], v[46:47], 1.0 op_sel_hi:[1,0]
	v_pk_add_f32 v[40:41], v[40:41], 1.0 op_sel_hi:[1,0]
	v_pk_add_f32 v[42:43], v[42:43], 1.0 op_sel_hi:[1,0]
	v_pk_add_f32 v[36:37], v[36:37], 1.0 op_sel_hi:[1,0]
	v_pk_add_f32 v[38:39], v[38:39], 1.0 op_sel_hi:[1,0]
	v_pk_add_f32 v[32:33], v[32:33], 1.0 op_sel_hi:[1,0]
	v_pk_add_f32 v[34:35], v[34:35], 1.0 op_sel_hi:[1,0]
	v_max_f32_e32 v28, s18, v28
	v_max_f32_e32 v29, s18, v29
; DI unsigned pk2(float lo, float hi) { f32x2 v = {lo, hi}; bf16x2_t b = __builtin_convertvector(v, bf16x2_t); return __builtin_bit_cast(unsigned, b); }
; DI unsigned ror8(unsigned x) { return (unsigned)__builtin_amdgcn_mov_dpp((int)x, 0x128, 0xf, 0xf, true); }
; DI void store_lines(bf16_t* Ob, size_t row, int ldc, int colw, int fr, int fq, const u32x4& w0, const u32x4& w1) {
;     const bool lo = (fr & 8) == 0;
;     const u32x4 snd = lo ? w1 : w0;
;     u32x4 rcv; rcv.x = ror8(snd.x); rcv.y = ror8(snd.y); rcv.z = ror8(snd.z); rcv.w = ror8(snd.w);
;     const u32x4 dA = lo ? w0 : rcv, dB = lo ? rcv : w1;
;     const int col = colw + 8 * fq + (lo ? 0 : 32);
;     __builtin_nontemporal_store(dA, (u32x4*)(Ob + (lo ? row : row - 8) * ldc + col));
;     __builtin_nontemporal_store(dB, (u32x4*)(Ob + (lo ? row + 8 : row) * ldc + col));
; DI void epilogue(const f32x4 (&acc)[2][2][4][2], int ph, unsigned char* ws, const float* pscale, const Unit& u, int wr, int wc, int fr, int fq) {
;     ...
;                 for (int bj = 0; bj < 2; ++bj) { f32x4 v0 = acc[ai][bj][m][0], v1 = acc[ai][bj][m][1];
;                     if (gateD) {
; #pragma unroll
;                         for (int j = 0; j < 4; ++j) { v0[j] = 1.0f + __builtin_amdgcn_exp2f(-fmaxf(v0[j], -30.f) * LOG2E); v1[j] = 1.0f + __builtin_amdgcn_exp2f(-fmaxf(v1[j], -30.f) * LOG2E); } }
;                     if (r2) {
; #pragma unroll
;                         for (int j = 0; j < 4; ++j) { const float a = fmaxf(v0[j], 0.f), b = fmaxf(v1[j], 0.f); v0[j] = a * a; v1[j] = b * b; } }
;                     w[bj].x = pk2(v0[0], v0[1]); w[bj].y = pk2(v0[2], v0[3]); w[bj].z = pk2(v1[0], v1[1]); w[bj].w = pk2(v1[2], v1[3]); }
;                 store_lines(Ob, (size_t)(row0 + ai * HALF + m * 16), ldc, colw, fr, fq, w[0], w[1]); }
	v_max_f32_e32 v30, s18, v30
	v_max_f32_e32 v31, s18, v31
	v_max_f32_e32 v24, s18, v24
	v_max_f32_e32 v25, s18, v25
	v_max_f32_e32 v26, s18, v26
	v_max_f32_e32 v27, s18, v27
	v_max_f32_e32 v20, s18, v20
	v_max_f32_e32 v21, s18, v21
	v_max_f32_e32 v22, s18, v22
	v_max_f32_e32 v23, s18, v23
	v_max_f32_e32 v16, s18, v16
	v_max_f32_e32 v17, s18, v17
	v_max_f32_e32 v18, s18, v18
	v_max_f32_e32 v19, s18, v19
	v_mul_f32_e32 v28, s19, v28
	v_mul_f32_e32 v29, s19, v29
	v_mul_f32_e32 v30, s19, v30
	v_mul_f32_e32 v31, s19, v31
	v_mul_f32_e32 v24, s19, v24
	v_mul_f32_e32 v25, s19, v25
	v_mul_f32_e32 v26, s19, v26
	v_mul_f32_e32 v27, s19, v27
	v_mul_f32_e32 v20, s19, v20
	v_mul_f32_e32 v21, s19, v21
	v_mul_f32_e32 v22, s19, v22
	v_mul_f32_e32 v23, s19, v23
	v_mul_f32_e32 v16, s19, v16
	v_mul_f32_e32 v17, s19, v17
	v_mul_f32_e32 v18, s19, v18
	v_mul_f32_e32 v19, s19, v19
	v_exp_f32_e32 v28, v28
	v_exp_f32_e32 v29, v29
	v_exp_f32_e32 v30, v30
	v_exp_f32_e32 v31, v31
	v_exp_f32_e32 v24, v24
	v_exp_f32_e32 v25, v25
	v_exp_f32_e32 v26, v26
	v_exp_f32_e32 v27, v27
	v_exp_f32_e32 v20, v20
	v_exp_f32_e32 v21, v21
	v_exp_f32_e32 v22, v22
	v_exp_f32_e32 v23, v23
	v_exp_f32_e32 v16, v16
	v_exp_f32_e32 v17, v17
	v_exp_f32_e32 v18, v18
	v_exp_f32_e32 v19, v19
	v_cvt_pk_bf16_f32 v44, v44, v45
	v_cvt_pk_bf16_f32 v45, v46, v47
	v_cvt_pk_bf16_f32 v46, v40, v41
	v_cvt_pk_bf16_f32 v47, v42, v43
	v_cvt_pk_bf16_f32 v36, v36, v37
	v_cvt_pk_bf16_f32 v37, v38, v39
	v_cvt_pk_bf16_f32 v38, v32, v33
	v_cvt_pk_bf16_f32 v39, v34, v35
	v_mov_b32_e32 v132, v44
	v_mov_b32_e32 v133, v45
	v_mov_b32_e32 v134, v46
	v_mov_b32_e32 v135, v47
	v_mov_b32_dpp v44, v36 row_ror:8 row_mask:0xf bank_mask:0xc
	v_mov_b32_dpp v45, v37 row_ror:8 row_mask:0xf bank_mask:0xc
	v_mov_b32_dpp v46, v38 row_ror:8 row_mask:0xf bank_mask:0xc
	v_mov_b32_dpp v47, v39 row_ror:8 row_mask:0xf bank_mask:0xc
	v_mov_b32_dpp v36, v132 row_ror:8 row_mask:0xf bank_mask:0x3
	v_mov_b32_dpp v37, v133 row_ror:8 row_mask:0xf bank_mask:0x3
	v_mov_b32_dpp v38, v134 row_ror:8 row_mask:0xf bank_mask:0x3
	v_mov_b32_dpp v39, v135 row_ror:8 row_mask:0xf bank_mask:0x3
	global_store_dwordx4 v[146:147], v[44:47], off nt
	v_lshl_add_u64 v[146:147], v[146:147], 0, s[38:39]
	global_store_dwordx4 v[146:147], v[36:39], off nt
	v_lshl_add_u64 v[146:147], v[146:147], 0, s[38:39]
	v_pk_add_f32 v[28:29], v[28:29], 1.0 op_sel_hi:[1,0]
	v_pk_add_f32 v[30:31], v[30:31], 1.0 op_sel_hi:[1,0]
	v_pk_add_f32 v[24:25], v[24:25], 1.0 op_sel_hi:[1,0]
	v_pk_add_f32 v[26:27], v[26:27], 1.0 op_sel_hi:[1,0]
	v_pk_add_f32 v[20:21], v[20:21], 1.0 op_sel_hi:[1,0]
	v_pk_add_f32 v[22:23], v[22:23], 1.0 op_sel_hi:[1,0]
	v_pk_add_f32 v[16:17], v[16:17], 1.0 op_sel_hi:[1,0]
	v_pk_add_f32 v[18:19], v[18:19], 1.0 op_sel_hi:[1,0]
	v_max_f32_e32 v12, s18, v12
	v_max_f32_e32 v13, s18, v13
	v_max_f32_e32 v14, s18, v14
	v_max_f32_e32 v15, s18, v15
	v_max_f32_e32 v8, s18, v8
	v_max_f32_e32 v9, s18, v9
	v_max_f32_e32 v10, s18, v10
	v_max_f32_e32 v11, s18, v11
	v_max_f32_e32 v4, s18, v4
	v_max_f32_e32 v5, s18, v5
	v_max_f32_e32 v6, s18, v6
	v_max_f32_e32 v7, s18, v7
	v_max_f32_e32 v0, s18, v0
	v_max_f32_e32 v1, s18, v1
	v_max_f32_e32 v2, s18, v2
	v_max_f32_e32 v3, s18, v3
	v_mul_f32_e32 v12, s19, v12
	v_mul_f32_e32 v13, s19, v13
	v_mul_f32_e32 v14, s19, v14
	v_mul_f32_e32 v15, s19, v15
	v_mul_f32_e32 v8, s19, v8
	v_mul_f32_e32 v9, s19, v9
	v_mul_f32_e32 v10, s19, v10
	v_mul_f32_e32 v11, s19, v11
	v_mul_f32_e32 v4, s19, v4
	v_mul_f32_e32 v5, s19, v5
	v_mul_f32_e32 v6, s19, v6
	v_mul_f32_e32 v7, s19, v7
	v_mul_f32_e32 v0, s19, v0
	v_mul_f32_e32 v1, s19, v1
	v_mul_f32_e32 v2, s19, v2
	v_mul_f32_e32 v3, s19, v3
	v_exp_f32_e32 v12, v12
	v_exp_f32_e32 v13, v13
	v_exp_f32_e32 v14, v14
	v_exp_f32_e32 v15, v15
	v_exp_f32_e32 v8, v8
	v_exp_f32_e32 v9, v9
	v_exp_f32_e32 v10, v10
	v_exp_f32_e32 v11, v11
	v_exp_f32_e32 v4, v4
	v_exp_f32_e32 v5, v5
	v_exp_f32_e32 v6, v6
	v_exp_f32_e32 v7, v7
	v_exp_f32_e32 v0, v0
	v_exp_f32_e32 v1, v1
	v_exp_f32_e32 v2, v2
	v_exp_f32_e32 v3, v3
	v_cvt_pk_bf16_f32 v28, v28, v29
	v_cvt_pk_bf16_f32 v29, v30, v31
	v_cvt_pk_bf16_f32 v30, v24, v25
	v_cvt_pk_bf16_f32 v31, v26, v27
	v_cvt_pk_bf16_f32 v20, v20, v21
	v_cvt_pk_bf16_f32 v21, v22, v23
	v_cvt_pk_bf16_f32 v22, v16, v17
	v_cvt_pk_bf16_f32 v23, v18, v19
	v_mov_b32_e32 v132, v28
	v_mov_b32_e32 v133, v29
	v_mov_b32_e32 v134, v30
	v_mov_b32_e32 v135, v31
	v_mov_b32_dpp v28, v20 row_ror:8 row_mask:0xf bank_mask:0xc
	v_mov_b32_dpp v29, v21 row_ror:8 row_mask:0xf bank_mask:0xc
	v_mov_b32_dpp v30, v22 row_ror:8 row_mask:0xf bank_mask:0xc
	v_mov_b32_dpp v31, v23 row_ror:8 row_mask:0xf bank_mask:0xc
	v_mov_b32_dpp v20, v132 row_ror:8 row_mask:0xf bank_mask:0x3
	v_mov_b32_dpp v21, v133 row_ror:8 row_mask:0xf bank_mask:0x3
	v_mov_b32_dpp v22, v134 row_ror:8 row_mask:0xf bank_mask:0x3
	v_mov_b32_dpp v23, v135 row_ror:8 row_mask:0xf bank_mask:0x3
	global_store_dwordx4 v[146:147], v[28:31], off nt
	v_lshl_add_u64 v[146:147], v[146:147], 0, s[38:39]
	global_store_dwordx4 v[146:147], v[20:23], off nt
	v_lshl_add_u64 v[146:147], v[146:147], 0, s[38:39]
	v_pk_add_f32 v[12:13], v[12:13], 1.0 op_sel_hi:[1,0]
	v_pk_add_f32 v[14:15], v[14:15], 1.0 op_sel_hi:[1,0]
	v_pk_add_f32 v[8:9], v[8:9], 1.0 op_sel_hi:[1,0]
	v_pk_add_f32 v[10:11], v[10:11], 1.0 op_sel_hi:[1,0]
	v_pk_add_f32 v[4:5], v[4:5], 1.0 op_sel_hi:[1,0]
	v_pk_add_f32 v[6:7], v[6:7], 1.0 op_sel_hi:[1,0]
	v_pk_add_f32 v[0:1], v[0:1], 1.0 op_sel_hi:[1,0]
	v_pk_add_f32 v[2:3], v[2:3], 1.0 op_sel_hi:[1,0]
	v_cvt_pk_bf16_f32 v12, v12, v13
	v_cvt_pk_bf16_f32 v13, v14, v15
	v_cvt_pk_bf16_f32 v14, v8, v9
	v_cvt_pk_bf16_f32 v15, v10, v11
	v_cvt_pk_bf16_f32 v4, v4, v5
	v_cvt_pk_bf16_f32 v5, v6, v7
	v_cvt_pk_bf16_f32 v6, v0, v1
	v_cvt_pk_bf16_f32 v7, v2, v3
	v_mov_b32_e32 v132, v12
	v_mov_b32_e32 v133, v13
	v_mov_b32_e32 v134, v14
	v_mov_b32_e32 v135, v15
	v_mov_b32_dpp v12, v4 row_ror:8 row_mask:0xf bank_mask:0xc
	v_mov_b32_dpp v13, v5 row_ror:8 row_mask:0xf bank_mask:0xc
	v_mov_b32_dpp v14, v6 row_ror:8 row_mask:0xf bank_mask:0xc
	v_mov_b32_dpp v15, v7 row_ror:8 row_mask:0xf bank_mask:0xc
	v_mov_b32_dpp v4, v132 row_ror:8 row_mask:0xf bank_mask:0x3
	v_mov_b32_dpp v5, v133 row_ror:8 row_mask:0xf bank_mask:0x3
	v_mov_b32_dpp v6, v134 row_ror:8 row_mask:0xf bank_mask:0x3
	v_mov_b32_dpp v7, v135 row_ror:8 row_mask:0xf bank_mask:0x3
	global_store_dwordx4 v[146:147], v[12:15], off nt
	v_lshl_add_u64 v[146:147], v[146:147], 0, s[38:39]
	global_store_dwordx4 v[146:147], v[4:7], off nt
	s_branch .LBB0_545
; DI unsigned pk2(float lo, float hi) { f32x2 v = {lo, hi}; bf16x2_t b = __builtin_convertvector(v, bf16x2_t); return __builtin_bit_cast(unsigned, b); }
; DI unsigned ror8(unsigned x) { return (unsigned)__builtin_amdgcn_mov_dpp((int)x, 0x128, 0xf, 0xf, true); }
; DI void store_lines(bf16_t* Ob, size_t row, int ldc, int colw, int fr, int fq, const u32x4& w0, const u32x4& w1) {
;     const bool lo = (fr & 8) == 0;
;     const u32x4 snd = lo ? w1 : w0;
;     u32x4 rcv; rcv.x = ror8(snd.x); rcv.y = ror8(snd.y); rcv.z = ror8(snd.z); rcv.w = ror8(snd.w);
;     const u32x4 dA = lo ? w0 : rcv, dB = lo ? rcv : w1;
;     const int col = colw + 8 * fq + (lo ? 0 : 32);
;     __builtin_nontemporal_store(dA, (u32x4*)(Ob + (lo ? row : row - 8) * ldc + col));
;     __builtin_nontemporal_store(dB, (u32x4*)(Ob + (lo ? row + 8 : row) * ldc + col));
; DI void epilogue(const f32x4 (&acc)[2][2][4][2], int ph, unsigned char* ws, const float* pscale, const Unit& u, int wr, int wc, int fr, int fq) {
;     ...
;                     if (r2) {
; #pragma unroll
;                         for (int j = 0; j < 4; ++j) { const float a = fmaxf(v0[j], 0.f), b = fmaxf(v1[j], 0.f); v0[j] = a * a; v1[j] = b * b; } }
;                     w[bj].x = pk2(v0[0], v0[1]); w[bj].y = pk2(v0[2], v0[3]); w[bj].z = pk2(v1[0], v1[1]); w[bj].w = pk2(v1[2], v1[3]); }
;                 store_lines(Ob, (size_t)(row0 + ai * HALF + m * 16), ldc, colw, fr, fq, w[0], w[1]); }
.Lep_nogate:
	s_cmp_lg_u32 s68, 1
	s_cbranch_scc1 .Lep_norelu
	v_and_b32_e32 v83, 8, v80
	v_sub_u32_e32 v175, v82, v83
	v_lshlrev_b32_e32 v83, 2, v83
	v_or3_b32 v132, v83, s66, v172
	v_ashrrev_i32_e32 v133, 31, v132
	v_lshl_add_u64 v[136:137], v[132:133], 1, s[40:41]
	v_mad_u64_u32 v[146:147], s[0:1], s64, v175, 0
	s_lshl_b32 s38, s64, 4
	s_mov_b32 s39, 0
	s_lshl_b32 s42, s64, 7
	s_mov_b32 s43, 0
	v_lshl_add_u64 v[146:147], v[146:147], 1, v[136:137]
	v_max_f32_e32 v128, 0, v128
	v_max_f32_e32 v129, 0, v129
	v_max_f32_e32 v130, 0, v130
	v_max_f32_e32 v131, 0, v131
	v_max_f32_e32 v124, 0, v124
	v_max_f32_e32 v125, 0, v125
	v_max_f32_e32 v126, 0, v126
	v_max_f32_e32 v127, 0, v127
	v_max_f32_e32 v120, 0, v120
	v_max_f32_e32 v121, 0, v121
	v_max_f32_e32 v122, 0, v122
	v_max_f32_e32 v123, 0, v123
	v_max_f32_e32 v116, 0, v116
	v_max_f32_e32 v117, 0, v117
	v_max_f32_e32 v118, 0, v118
	v_max_f32_e32 v119, 0, v119
	v_pk_mul_f32 v[128:129], v[128:129], v[128:129]
	v_pk_mul_f32 v[130:131], v[130:131], v[130:131]
	v_pk_mul_f32 v[124:125], v[124:125], v[124:125]
	v_pk_mul_f32 v[126:127], v[126:127], v[126:127]
	v_pk_mul_f32 v[120:121], v[120:121], v[120:121]
	v_pk_mul_f32 v[122:123], v[122:123], v[122:123]
	v_pk_mul_f32 v[116:117], v[116:117], v[116:117]
	v_pk_mul_f32 v[118:119], v[118:119], v[118:119]
	v_max_f32_e32 v112, 0, v112
	v_max_f32_e32 v113, 0, v113
	v_max_f32_e32 v114, 0, v114
	v_max_f32_e32 v115, 0, v115
	v_max_f32_e32 v108, 0, v108
	v_max_f32_e32 v109, 0, v109
	v_max_f32_e32 v110, 0, v110
	v_max_f32_e32 v111, 0, v111
	v_max_f32_e32 v104, 0, v104
	v_max_f32_e32 v105, 0, v105
	v_max_f32_e32 v106, 0, v106
	v_max_f32_e32 v107, 0, v107
	v_max_f32_e32 v100, 0, v100
	v_max_f32_e32 v101, 0, v101
	v_max_f32_e32 v102, 0, v102
	v_max_f32_e32 v103, 0, v103
	v_pk_mul_f32 v[112:113], v[112:113], v[112:113]
	v_pk_mul_f32 v[114:115], v[114:115], v[114:115]
	v_pk_mul_f32 v[108:109], v[108:109], v[108:109]
	v_pk_mul_f32 v[110:111], v[110:111], v[110:111]
	v_pk_mul_f32 v[104:105], v[104:105], v[104:105]
	v_pk_mul_f32 v[106:107], v[106:107], v[106:107]
	v_pk_mul_f32 v[100:101], v[100:101], v[100:101]
	v_pk_mul_f32 v[102:103], v[102:103], v[102:103]
	v_cvt_pk_bf16_f32 v128, v128, v129
	v_cvt_pk_bf16_f32 v129, v130, v131
	v_cvt_pk_bf16_f32 v130, v124, v125
	v_cvt_pk_bf16_f32 v131, v126, v127
	v_cvt_pk_bf16_f32 v120, v120, v121
	v_cvt_pk_bf16_f32 v121, v122, v123
	v_cvt_pk_bf16_f32 v122, v116, v117
	v_cvt_pk_bf16_f32 v123, v118, v119
	v_mov_b32_e32 v132, v128
	v_mov_b32_e32 v133, v129
	v_mov_b32_e32 v134, v130
	v_mov_b32_e32 v135, v131
	v_mov_b32_dpp v128, v120 row_ror:8 row_mask:0xf bank_mask:0xc
	v_mov_b32_dpp v129, v121 row_ror:8 row_mask:0xf bank_mask:0xc
	v_mov_b32_dpp v130, v122 row_ror:8 row_mask:0xf bank_mask:0xc
	v_mov_b32_dpp v131, v123 row_ror:8 row_mask:0xf bank_mask:0xc
	v_mov_b32_dpp v120, v132 row_ror:8 row_mask:0xf bank_mask:0x3
	v_mov_b32_dpp v121, v133 row_ror:8 row_mask:0xf bank_mask:0x3
	v_mov_b32_dpp v122, v134 row_ror:8 row_mask:0xf bank_mask:0x3
	v_mov_b32_dpp v123, v135 row_ror:8 row_mask:0xf bank_mask:0x3
	global_store_dwordx4 v[146:147], v[128:131], off nt
	v_lshl_add_u64 v[146:147], v[146:147], 0, s[38:39]
	global_store_dwordx4 v[146:147], v[120:123], off nt
	v_lshl_add_u64 v[146:147], v[146:147], 0, s[38:39]
	v_max_f32_e32 v96, 0, v96
	v_max_f32_e32 v97, 0, v97
	v_max_f32_e32 v98, 0, v98
	v_max_f32_e32 v99, 0, v99
	v_max_f32_e32 v92, 0, v92
	v_max_f32_e32 v93, 0, v93
	v_max_f32_e32 v94, 0, v94
	v_max_f32_e32 v95, 0, v95
	v_max_f32_e32 v88, 0, v88
	v_max_f32_e32 v89, 0, v89
	v_max_f32_e32 v90, 0, v90
	v_max_f32_e32 v91, 0, v91
	v_max_f32_e32 v84, 0, v84
	v_max_f32_e32 v85, 0, v85
	v_max_f32_e32 v86, 0, v86
	v_max_f32_e32 v87, 0, v87
	v_pk_mul_f32 v[96:97], v[96:97], v[96:97]
	v_pk_mul_f32 v[98:99], v[98:99], v[98:99]
	v_pk_mul_f32 v[92:93], v[92:93], v[92:93]
	v_pk_mul_f32 v[94:95], v[94:95], v[94:95]
	v_pk_mul_f32 v[88:89], v[88:89], v[88:89]
	v_pk_mul_f32 v[90:91], v[90:91], v[90:91]
	v_pk_mul_f32 v[84:85], v[84:85], v[84:85]
	v_pk_mul_f32 v[86:87], v[86:87], v[86:87]
	v_cvt_pk_bf16_f32 v112, v112, v113
	v_cvt_pk_bf16_f32 v113, v114, v115
	v_cvt_pk_bf16_f32 v114, v108, v109
	v_cvt_pk_bf16_f32 v115, v110, v111
	v_cvt_pk_bf16_f32 v104, v104, v105
	v_cvt_pk_bf16_f32 v105, v106, v107
	v_cvt_pk_bf16_f32 v106, v100, v101
	v_cvt_pk_bf16_f32 v107, v102, v103
	v_mov_b32_e32 v132, v112
	v_mov_b32_e32 v133, v113
	v_mov_b32_e32 v134, v114
	v_mov_b32_e32 v135, v115
	v_mov_b32_dpp v112, v104 row_ror:8 row_mask:0xf bank_mask:0xc
	v_mov_b32_dpp v113, v105 row_ror:8 row_mask:0xf bank_mask:0xc
	v_mov_b32_dpp v114, v106 row_ror:8 row_mask:0xf bank_mask:0xc
	v_mov_b32_dpp v115, v107 row_ror:8 row_mask:0xf bank_mask:0xc
	v_mov_b32_dpp v104, v132 row_ror:8 row_mask:0xf bank_mask:0x3
	v_mov_b32_dpp v105, v133 row_ror:8 row_mask:0xf bank_mask:0x3
	v_mov_b32_dpp v106, v134 row_ror:8 row_mask:0xf bank_mask:0x3
	v_mov_b32_dpp v107, v135 row_ror:8 row_mask:0xf bank_mask:0x3
	global_store_dwordx4 v[146:147], v[112:115], off nt
	v_lshl_add_u64 v[146:147], v[146:147], 0, s[38:39]
	global_store_dwordx4 v[146:147], v[104:107], off nt
	v_lshl_add_u64 v[146:147], v[146:147], 0, s[38:39]
	v_max_f32_e32 v76, 0, v76
	v_max_f32_e32 v77, 0, v77
	v_max_f32_e32 v78, 0, v78
	v_max_f32_e32 v79, 0, v79
	v_max_f32_e32 v72, 0, v72
	v_max_f32_e32 v73, 0, v73
	v_max_f32_e32 v74, 0, v74
	v_max_f32_e32 v75, 0, v75
	v_max_f32_e32 v68, 0, v68
	v_max_f32_e32 v69, 0, v69
	v_max_f32_e32 v70, 0, v70
	v_max_f32_e32 v71, 0, v71
	v_max_f32_e32 v64, 0, v64
	v_max_f32_e32 v65, 0, v65
	v_max_f32_e32 v66, 0, v66
	v_max_f32_e32 v67, 0, v67
	v_pk_mul_f32 v[76:77], v[76:77], v[76:77]
; DI unsigned pk2(float lo, float hi) { f32x2 v = {lo, hi}; bf16x2_t b = __builtin_convertvector(v, bf16x2_t); return __builtin_bit_cast(unsigned, b); }
; DI unsigned ror8(unsigned x) { return (unsigned)__builtin_amdgcn_mov_dpp((int)x, 0x128, 0xf, 0xf, true); }
; DI void store_lines(bf16_t* Ob, size_t row, int ldc, int colw, int fr, int fq, const u32x4& w0, const u32x4& w1) {
;     const bool lo = (fr & 8) == 0;
;     const u32x4 snd = lo ? w1 : w0;
;     u32x4 rcv; rcv.x = ror8(snd.x); rcv.y = ror8(snd.y); rcv.z = ror8(snd.z); rcv.w = ror8(snd.w);
;     const u32x4 dA = lo ? w0 : rcv, dB = lo ? rcv : w1;
;     const int col = colw + 8 * fq + (lo ? 0 : 32);
;     __builtin_nontemporal_store(dA, (u32x4*)(Ob + (lo ? row : row - 8) * ldc + col));
;     __builtin_nontemporal_store(dB, (u32x4*)(Ob + (lo ? row + 8 : row) * ldc + col));
; DI void epilogue(const f32x4 (&acc)[2][2][4][2], int ph, unsigned char* ws, const float* pscale, const Unit& u, int wr, int wc, int fr, int fq) {
;     ...
;                     if (r2) {
; #pragma unroll
;                         for (int j = 0; j < 4; ++j) { const float a = fmaxf(v0[j], 0.f), b = fmaxf(v1[j], 0.f); v0[j] = a * a; v1[j] = b * b; } }
;                     w[bj].x = pk2(v0[0], v0[1]); w[bj].y = pk2(v0[2], v0[3]); w[bj].z = pk2(v1[0], v1[1]); w[bj].w = pk2(v1[2], v1[3]); }
;                 store_lines(Ob, (size_t)(row0 + ai * HALF + m * 16), ldc, colw, fr, fq, w[0], w[1]); }
	v_pk_mul_f32 v[78:79], v[78:79], v[78:79]
	v_pk_mul_f32 v[72:73], v[72:73], v[72:73]
	v_pk_mul_f32 v[74:75], v[74:75], v[74:75]
	v_pk_mul_f32 v[68:69], v[68:69], v[68:69]
	v_pk_mul_f32 v[70:71], v[70:71], v[70:71]
	v_pk_mul_f32 v[64:65], v[64:65], v[64:65]
	v_pk_mul_f32 v[66:67], v[66:67], v[66:67]
	v_cvt_pk_bf16_f32 v96, v96, v97
	v_cvt_pk_bf16_f32 v97, v98, v99
	v_cvt_pk_bf16_f32 v98, v92, v93
	v_cvt_pk_bf16_f32 v99, v94, v95
	v_cvt_pk_bf16_f32 v88, v88, v89
	v_cvt_pk_bf16_f32 v89, v90, v91
	v_cvt_pk_bf16_f32 v90, v84, v85
	v_cvt_pk_bf16_f32 v91, v86, v87
	v_mov_b32_e32 v132, v96
	v_mov_b32_e32 v133, v97
	v_mov_b32_e32 v134, v98
	v_mov_b32_e32 v135, v99
	v_mov_b32_dpp v96, v88 row_ror:8 row_mask:0xf bank_mask:0xc
	v_mov_b32_dpp v97, v89 row_ror:8 row_mask:0xf bank_mask:0xc
	v_mov_b32_dpp v98, v90 row_ror:8 row_mask:0xf bank_mask:0xc
	v_mov_b32_dpp v99, v91 row_ror:8 row_mask:0xf bank_mask:0xc
	v_mov_b32_dpp v88, v132 row_ror:8 row_mask:0xf bank_mask:0x3
	v_mov_b32_dpp v89, v133 row_ror:8 row_mask:0xf bank_mask:0x3
	v_mov_b32_dpp v90, v134 row_ror:8 row_mask:0xf bank_mask:0x3
	v_mov_b32_dpp v91, v135 row_ror:8 row_mask:0xf bank_mask:0x3
	global_store_dwordx4 v[146:147], v[96:99], off nt
	v_lshl_add_u64 v[146:147], v[146:147], 0, s[38:39]
	global_store_dwordx4 v[146:147], v[88:91], off nt
	v_lshl_add_u64 v[146:147], v[146:147], 0, s[38:39]
	v_max_f32_e32 v60, 0, v60
	v_max_f32_e32 v61, 0, v61
	v_max_f32_e32 v62, 0, v62
	v_max_f32_e32 v63, 0, v63
	v_max_f32_e32 v56, 0, v56
	v_max_f32_e32 v57, 0, v57
	v_max_f32_e32 v58, 0, v58
	v_max_f32_e32 v59, 0, v59
	v_max_f32_e32 v52, 0, v52
	v_max_f32_e32 v53, 0, v53
	v_max_f32_e32 v54, 0, v54
	v_max_f32_e32 v55, 0, v55
	v_max_f32_e32 v48, 0, v48
	v_max_f32_e32 v49, 0, v49
	v_max_f32_e32 v50, 0, v50
	v_max_f32_e32 v51, 0, v51
	v_pk_mul_f32 v[60:61], v[60:61], v[60:61]
	v_pk_mul_f32 v[62:63], v[62:63], v[62:63]
	v_pk_mul_f32 v[56:57], v[56:57], v[56:57]
	v_pk_mul_f32 v[58:59], v[58:59], v[58:59]
	v_pk_mul_f32 v[52:53], v[52:53], v[52:53]
	v_pk_mul_f32 v[54:55], v[54:55], v[54:55]
	v_pk_mul_f32 v[48:49], v[48:49], v[48:49]
	v_pk_mul_f32 v[50:51], v[50:51], v[50:51]
	v_cvt_pk_bf16_f32 v76, v76, v77
	v_cvt_pk_bf16_f32 v77, v78, v79
	v_cvt_pk_bf16_f32 v78, v72, v73
	v_cvt_pk_bf16_f32 v79, v74, v75
	v_cvt_pk_bf16_f32 v68, v68, v69
	v_cvt_pk_bf16_f32 v69, v70, v71
	v_cvt_pk_bf16_f32 v70, v64, v65
	v_cvt_pk_bf16_f32 v71, v66, v67
	v_mov_b32_e32 v132, v76
	v_mov_b32_e32 v133, v77
	v_mov_b32_e32 v134, v78
	v_mov_b32_e32 v135, v79
	v_mov_b32_dpp v76, v68 row_ror:8 row_mask:0xf bank_mask:0xc
	v_mov_b32_dpp v77, v69 row_ror:8 row_mask:0xf bank_mask:0xc
	v_mov_b32_dpp v78, v70 row_ror:8 row_mask:0xf bank_mask:0xc
	v_mov_b32_dpp v79, v71 row_ror:8 row_mask:0xf bank_mask:0xc
	v_mov_b32_dpp v68, v132 row_ror:8 row_mask:0xf bank_mask:0x3
	v_mov_b32_dpp v69, v133 row_ror:8 row_mask:0xf bank_mask:0x3
	v_mov_b32_dpp v70, v134 row_ror:8 row_mask:0xf bank_mask:0x3
	v_mov_b32_dpp v71, v135 row_ror:8 row_mask:0xf bank_mask:0x3
	global_store_dwordx4 v[146:147], v[76:79], off nt
	v_lshl_add_u64 v[146:147], v[146:147], 0, s[38:39]
	global_store_dwordx4 v[146:147], v[68:71], off nt
	v_lshl_add_u64 v[146:147], v[146:147], 0, s[38:39]
	v_lshl_add_u64 v[146:147], v[146:147], 0, s[42:43]
	v_max_f32_e32 v44, 0, v44
	v_max_f32_e32 v45, 0, v45
	v_max_f32_e32 v46, 0, v46
	v_max_f32_e32 v47, 0, v47
	v_max_f32_e32 v40, 0, v40
	v_max_f32_e32 v41, 0, v41
	v_max_f32_e32 v42, 0, v42
	v_max_f32_e32 v43, 0, v43
	v_max_f32_e32 v36, 0, v36
	v_max_f32_e32 v37, 0, v37
	v_max_f32_e32 v38, 0, v38
	v_max_f32_e32 v39, 0, v39
	v_max_f32_e32 v32, 0, v32
	v_max_f32_e32 v33, 0, v33
	v_max_f32_e32 v34, 0, v34
	v_max_f32_e32 v35, 0, v35
	v_pk_mul_f32 v[44:45], v[44:45], v[44:45]
	v_pk_mul_f32 v[46:47], v[46:47], v[46:47]
	v_pk_mul_f32 v[40:41], v[40:41], v[40:41]
	v_pk_mul_f32 v[42:43], v[42:43], v[42:43]
	v_pk_mul_f32 v[36:37], v[36:37], v[36:37]
	v_pk_mul_f32 v[38:39], v[38:39], v[38:39]
	v_pk_mul_f32 v[32:33], v[32:33], v[32:33]
	v_pk_mul_f32 v[34:35], v[34:35], v[34:35]
	v_cvt_pk_bf16_f32 v60, v60, v61
	v_cvt_pk_bf16_f32 v61, v62, v63
	v_cvt_pk_bf16_f32 v62, v56, v57
	v_cvt_pk_bf16_f32 v63, v58, v59
	v_cvt_pk_bf16_f32 v52, v52, v53
	v_cvt_pk_bf16_f32 v53, v54, v55
	v_cvt_pk_bf16_f32 v54, v48, v49
	v_cvt_pk_bf16_f32 v55, v50, v51
	v_mov_b32_e32 v132, v60
	v_mov_b32_e32 v133, v61
	v_mov_b32_e32 v134, v62
	v_mov_b32_e32 v135, v63
	v_mov_b32_dpp v60, v52 row_ror:8 row_mask:0xf bank_mask:0xc
	v_mov_b32_dpp v61, v53 row_ror:8 row_mask:0xf bank_mask:0xc
	v_mov_b32_dpp v62, v54 row_ror:8 row_mask:0xf bank_mask:0xc
	v_mov_b32_dpp v63, v55 row_ror:8 row_mask:0xf bank_mask:0xc
	v_mov_b32_dpp v52, v132 row_ror:8 row_mask:0xf bank_mask:0x3
	v_mov_b32_dpp v53, v133 row_ror:8 row_mask:0xf bank_mask:0x3
	v_mov_b32_dpp v54, v134 row_ror:8 row_mask:0xf bank_mask:0x3
	v_mov_b32_dpp v55, v135 row_ror:8 row_mask:0xf bank_mask:0x3
; DI unsigned pk2(float lo, float hi) { f32x2 v = {lo, hi}; bf16x2_t b = __builtin_convertvector(v, bf16x2_t); return __builtin_bit_cast(unsigned, b); }
; DI unsigned ror8(unsigned x) { return (unsigned)__builtin_amdgcn_mov_dpp((int)x, 0x128, 0xf, 0xf, true); }
; DI void store_lines(bf16_t* Ob, size_t row, int ldc, int colw, int fr, int fq, const u32x4& w0, const u32x4& w1) {
;     const bool lo = (fr & 8) == 0;
;     const u32x4 snd = lo ? w1 : w0;
;     u32x4 rcv; rcv.x = ror8(snd.x); rcv.y = ror8(snd.y); rcv.z = ror8(snd.z); rcv.w = ror8(snd.w);
;     const u32x4 dA = lo ? w0 : rcv, dB = lo ? rcv : w1;
;     const int col = colw + 8 * fq + (lo ? 0 : 32);
;     __builtin_nontemporal_store(dA, (u32x4*)(Ob + (lo ? row : row - 8) * ldc + col));
;     __builtin_nontemporal_store(dB, (u32x4*)(Ob + (lo ? row + 8 : row) * ldc + col));
; DI void epilogue(const f32x4 (&acc)[2][2][4][2], int ph, unsigned char* ws, const float* pscale, const Unit& u, int wr, int wc, int fr, int fq) {
;     ...
;                     if (r2) {
; #pragma unroll
;                         for (int j = 0; j < 4; ++j) { const float a = fmaxf(v0[j], 0.f), b = fmaxf(v1[j], 0.f); v0[j] = a * a; v1[j] = b * b; } }
;                     w[bj].x = pk2(v0[0], v0[1]); w[bj].y = pk2(v0[2], v0[3]); w[bj].z = pk2(v1[0], v1[1]); w[bj].w = pk2(v1[2], v1[3]); }
;                 store_lines(Ob, (size_t)(row0 + ai * HALF + m * 16), ldc, colw, fr, fq, w[0], w[1]); }
	global_store_dwordx4 v[146:147], v[60:63], off nt
	v_lshl_add_u64 v[146:147], v[146:147], 0, s[38:39]
	global_store_dwordx4 v[146:147], v[52:55], off nt
	v_lshl_add_u64 v[146:147], v[146:147], 0, s[38:39]
	v_max_f32_e32 v28, 0, v28
	v_max_f32_e32 v29, 0, v29
	v_max_f32_e32 v30, 0, v30
	v_max_f32_e32 v31, 0, v31
	v_max_f32_e32 v24, 0, v24
	v_max_f32_e32 v25, 0, v25
	v_max_f32_e32 v26, 0, v26
	v_max_f32_e32 v27, 0, v27
	v_max_f32_e32 v20, 0, v20
	v_max_f32_e32 v21, 0, v21
	v_max_f32_e32 v22, 0, v22
	v_max_f32_e32 v23, 0, v23
	v_max_f32_e32 v16, 0, v16
	v_max_f32_e32 v17, 0, v17
	v_max_f32_e32 v18, 0, v18
	v_max_f32_e32 v19, 0, v19
	v_pk_mul_f32 v[28:29], v[28:29], v[28:29]
	v_pk_mul_f32 v[30:31], v[30:31], v[30:31]
	v_pk_mul_f32 v[24:25], v[24:25], v[24:25]
	v_pk_mul_f32 v[26:27], v[26:27], v[26:27]
	v_pk_mul_f32 v[20:21], v[20:21], v[20:21]
	v_pk_mul_f32 v[22:23], v[22:23], v[22:23]
	v_pk_mul_f32 v[16:17], v[16:17], v[16:17]
	v_pk_mul_f32 v[18:19], v[18:19], v[18:19]
	v_cvt_pk_bf16_f32 v44, v44, v45
	v_cvt_pk_bf16_f32 v45, v46, v47
	v_cvt_pk_bf16_f32 v46, v40, v41
	v_cvt_pk_bf16_f32 v47, v42, v43
	v_cvt_pk_bf16_f32 v36, v36, v37
	v_cvt_pk_bf16_f32 v37, v38, v39
	v_cvt_pk_bf16_f32 v38, v32, v33
	v_cvt_pk_bf16_f32 v39, v34, v35
	v_mov_b32_e32 v132, v44
	v_mov_b32_e32 v133, v45
	v_mov_b32_e32 v134, v46
	v_mov_b32_e32 v135, v47
	v_mov_b32_dpp v44, v36 row_ror:8 row_mask:0xf bank_mask:0xc
	v_mov_b32_dpp v45, v37 row_ror:8 row_mask:0xf bank_mask:0xc
	v_mov_b32_dpp v46, v38 row_ror:8 row_mask:0xf bank_mask:0xc
	v_mov_b32_dpp v47, v39 row_ror:8 row_mask:0xf bank_mask:0xc
	v_mov_b32_dpp v36, v132 row_ror:8 row_mask:0xf bank_mask:0x3
	v_mov_b32_dpp v37, v133 row_ror:8 row_mask:0xf bank_mask:0x3
	v_mov_b32_dpp v38, v134 row_ror:8 row_mask:0xf bank_mask:0x3
	v_mov_b32_dpp v39, v135 row_ror:8 row_mask:0xf bank_mask:0x3
	global_store_dwordx4 v[146:147], v[44:47], off nt
	v_lshl_add_u64 v[146:147], v[146:147], 0, s[38:39]
	global_store_dwordx4 v[146:147], v[36:39], off nt
	v_lshl_add_u64 v[146:147], v[146:147], 0, s[38:39]
	v_max_f32_e32 v12, 0, v12
	v_max_f32_e32 v13, 0, v13
	v_max_f32_e32 v14, 0, v14
	v_max_f32_e32 v15, 0, v15
	v_max_f32_e32 v8, 0, v8
	v_max_f32_e32 v9, 0, v9
	v_max_f32_e32 v10, 0, v10
	v_max_f32_e32 v11, 0, v11
	v_max_f32_e32 v4, 0, v4
	v_max_f32_e32 v5, 0, v5
	v_max_f32_e32 v6, 0, v6
	v_max_f32_e32 v7, 0, v7
	v_max_f32_e32 v0, 0, v0
	v_max_f32_e32 v1, 0, v1
	v_max_f32_e32 v2, 0, v2
	v_max_f32_e32 v3, 0, v3
	v_pk_mul_f32 v[12:13], v[12:13], v[12:13]
	v_pk_mul_f32 v[14:15], v[14:15], v[14:15]
	v_pk_mul_f32 v[8:9], v[8:9], v[8:9]
	v_pk_mul_f32 v[10:11], v[10:11], v[10:11]
	v_pk_mul_f32 v[4:5], v[4:5], v[4:5]
	v_pk_mul_f32 v[6:7], v[6:7], v[6:7]
	v_pk_mul_f32 v[0:1], v[0:1], v[0:1]
	v_pk_mul_f32 v[2:3], v[2:3], v[2:3]
	v_cvt_pk_bf16_f32 v28, v28, v29
	v_cvt_pk_bf16_f32 v29, v30, v31
	v_cvt_pk_bf16_f32 v30, v24, v25
	v_cvt_pk_bf16_f32 v31, v26, v27
	v_cvt_pk_bf16_f32 v20, v20, v21
	v_cvt_pk_bf16_f32 v21, v22, v23
	v_cvt_pk_bf16_f32 v22, v16, v17
	v_cvt_pk_bf16_f32 v23, v18, v19
	v_mov_b32_e32 v132, v28
	v_mov_b32_e32 v133, v29
	v_mov_b32_e32 v134, v30
	v_mov_b32_e32 v135, v31
	v_mov_b32_dpp v28, v20 row_ror:8 row_mask:0xf bank_mask:0xc
	v_mov_b32_dpp v29, v21 row_ror:8 row_mask:0xf bank_mask:0xc
	v_mov_b32_dpp v30, v22 row_ror:8 row_mask:0xf bank_mask:0xc
	v_mov_b32_dpp v31, v23 row_ror:8 row_mask:0xf bank_mask:0xc
	v_mov_b32_dpp v20, v132 row_ror:8 row_mask:0xf bank_mask:0x3
	v_mov_b32_dpp v21, v133 row_ror:8 row_mask:0xf bank_mask:0x3
	v_mov_b32_dpp v22, v134 row_ror:8 row_mask:0xf bank_mask:0x3
	v_mov_b32_dpp v23, v135 row_ror:8 row_mask:0xf bank_mask:0x3
	global_store_dwordx4 v[146:147], v[28:31], off nt
	v_lshl_add_u64 v[146:147], v[146:147], 0, s[38:39]
	global_store_dwordx4 v[146:147], v[20:23], off nt
	v_lshl_add_u64 v[146:147], v[146:147], 0, s[38:39]
	v_cvt_pk_bf16_f32 v12, v12, v13
	v_cvt_pk_bf16_f32 v13, v14, v15
	v_cvt_pk_bf16_f32 v14, v8, v9
	v_cvt_pk_bf16_f32 v15, v10, v11
	v_cvt_pk_bf16_f32 v4, v4, v5
	v_cvt_pk_bf16_f32 v5, v6, v7
	v_cvt_pk_bf16_f32 v6, v0, v1
	v_cvt_pk_bf16_f32 v7, v2, v3
	v_mov_b32_e32 v132, v12
	v_mov_b32_e32 v133, v13
	v_mov_b32_e32 v134, v14
	v_mov_b32_e32 v135, v15
	v_mov_b32_dpp v12, v4 row_ror:8 row_mask:0xf bank_mask:0xc
	v_mov_b32_dpp v13, v5 row_ror:8 row_mask:0xf bank_mask:0xc
	v_mov_b32_dpp v14, v6 row_ror:8 row_mask:0xf bank_mask:0xc
	v_mov_b32_dpp v15, v7 row_ror:8 row_mask:0xf bank_mask:0xc
	v_mov_b32_dpp v4, v132 row_ror:8 row_mask:0xf bank_mask:0x3
	v_mov_b32_dpp v5, v133 row_ror:8 row_mask:0xf bank_mask:0x3
	v_mov_b32_dpp v6, v134 row_ror:8 row_mask:0xf bank_mask:0x3
	v_mov_b32_dpp v7, v135 row_ror:8 row_mask:0xf bank_mask:0x3
	global_store_dwordx4 v[146:147], v[12:15], off nt
	v_lshl_add_u64 v[146:147], v[146:147], 0, s[38:39]
	global_store_dwordx4 v[146:147], v[4:7], off nt
	s_branch .LBB0_545
